# plus: GU epilogue row-stat loads prefetched; SSD chunk prefix sum via DPP; RET and SSD Y stores widened to dwordx4 via permlane16_swap; LRU gate MFMAs pipelined
# speedup vs baseline: 1.0203x; 1.0074x over previous
; __device__ __forceinline__ unsigned pk2(float lo, float hi) { return pg8::cvt_pk_bf16(lo, hi); }
; __device__ __forceinline__ float siluf(float x) { return x * sigm(x); }
; __device__ __forceinline__ float row_rs4(const float* ssq, size_t row, int fq) {
;     const f32x4 a = *(const f32x4*)(ssq + row * 16 + 4 * fq);
;     float s = (a[0] + a[1]) + (a[2] + a[3]);
;     s += __shfl_xor(s, 16); s += __shfl_xor(s, 32);
;     return rsqrtf(s * (1.0f / DM) + EPSN);
; }
;     __device__ __forceinline__ void operator()(const pg8::f32x4 (&acc)[2][2][4][2], const pg8::Unit& u, int wr, int wc, int fr, int fq) const {
;         const int row0 = u.pm * 256 + wr * 64 + fr, col0 = u.pn * 128 + wc * 32 + 8 * fq;
; #pragma unroll
;         for (int ai = 0; ai < 2; ++ai)
; #pragma unroll
;             for (int m = 0; m < 4; ++m) {
;                 const size_t row = (size_t)(row0 + ai * 128 + m * 16);
;                 const float rs = row_rs4(ssq, row, fq);
;                 const pg8::f32x4 g0 = acc[ai][0][m][0] * rs, g1 = acc[ai][0][m][1] * rs, u0 = acc[ai][1][m][0] * rs, u1 = acc[ai][1][m][1] * rs;
;                 u32x4 w;
;                 w.x = pk2(siluf(g0[0]) * u0[0], siluf(g0[1]) * u0[1]); w.y = pk2(siluf(g0[2]) * u0[2], siluf(g0[3]) * u0[3]);
;                 w.z = pk2(siluf(g1[0]) * u1[0], siluf(g1[1]) * u1[1]); w.w = pk2(siluf(g1[2]) * u1[2], siluf(g1[3]) * u1[3]);
;                 *(u32x4*)(H + row * DFF + col0) = w;
;                 if (m == 3) asm volatile("" ::: "memory");
;             }
.LBB0_160:
	v_and_b32_e32 v147, 64, v175
	v_xor_b32_e32 v145, 16, v175
	v_add_u32_e32 v147, 64, v147
	v_cmp_lt_i32_e32 vcc, v145, v147
	v_lshl_add_u32 v144, s31, 8, v131
	s_mov_b32 s9, 0x800000
	v_cndmask_b32_e32 v145, v175, v145, vcc
	v_lshlrev_b32_e32 v151, 2, v145
	v_xor_b32_e32 v145, 32, v175
	v_cmp_lt_i32_e32 vcc, v145, v147
	v_readlane_b32 s34, v253, 38
	v_lshl_or_b32 v146, s30, 7, v149
	v_cndmask_b32_e32 v145, v175, v145, vcc
	v_lshlrev_b32_e32 v152, 2, v145
	v_ashrrev_i32_e32 v145, 31, v144
	v_lshlrev_b64 v[154:155], 6, v[144:145]
	v_lshl_add_u64 v[154:155], v[138:139], 0, v[154:155]
	global_load_dwordx4 v[154:157], v[154:155], off
	v_add_u32_e32 v232, 0x10, v144
	v_ashrrev_i32_e32 v233, 31, v232
	v_lshlrev_b64 v[232:233], 6, v[232:233]
	v_lshl_add_u64 v[232:233], v[138:139], 0, v[232:233]
	global_load_dwordx4 v[204:207], v[232:233], off
	v_add_u32_e32 v232, 0x20, v144
	v_ashrrev_i32_e32 v233, 31, v232
	v_lshlrev_b64 v[232:233], 6, v[232:233]
	v_lshl_add_u64 v[232:233], v[138:139], 0, v[232:233]
	global_load_dwordx4 v[208:211], v[232:233], off
	v_add_u32_e32 v232, 0x30, v144
	v_ashrrev_i32_e32 v233, 31, v232
	v_lshlrev_b64 v[232:233], 6, v[232:233]
	v_lshl_add_u64 v[232:233], v[138:139], 0, v[232:233]
	global_load_dwordx4 v[212:215], v[232:233], off
	v_add_u32_e32 v232, 0x80, v144
	v_ashrrev_i32_e32 v233, 31, v232
	v_lshlrev_b64 v[232:233], 6, v[232:233]
	v_lshl_add_u64 v[232:233], v[138:139], 0, v[232:233]
	global_load_dwordx4 v[216:219], v[232:233], off
	v_add_u32_e32 v232, 0x90, v144
	v_ashrrev_i32_e32 v233, 31, v232
	v_lshlrev_b64 v[232:233], 6, v[232:233]
	v_lshl_add_u64 v[232:233], v[138:139], 0, v[232:233]
	global_load_dwordx4 v[220:223], v[232:233], off
	v_add_u32_e32 v232, 0xa0, v144
	v_ashrrev_i32_e32 v233, 31, v232
	v_lshlrev_b64 v[232:233], 6, v[232:233]
	v_lshl_add_u64 v[232:233], v[138:139], 0, v[232:233]
	global_load_dwordx4 v[224:227], v[232:233], off
	v_add_u32_e32 v232, 0xb0, v144
	v_ashrrev_i32_e32 v233, 31, v232
	v_lshlrev_b64 v[232:233], 6, v[232:233]
	v_lshl_add_u64 v[232:233], v[138:139], 0, v[232:233]
	global_load_dwordx4 v[228:231], v[232:233], off
	v_readlane_b32 s35, v253, 39
	v_ashrrev_i32_e32 v147, 31, v146
	s_movk_i32 s11, 0x1600
	s_waitcnt vmcnt(0)
	v_mov_b32_e32 v158, v155
	v_mov_b32_e32 v159, v156
	v_mov_b32_e32 v155, v157
	v_pk_add_f32 v[154:155], v[158:159], v[154:155]
	s_nop 0
	v_add_f32_e32 v145, v154, v155
	ds_bpermute_b32 v153, v151, v145
	s_waitcnt lgkmcnt(0)
	v_add_f32_e32 v145, v145, v153
	ds_bpermute_b32 v153, v152, v145
	s_waitcnt lgkmcnt(0)
	v_add_f32_e32 v145, v145, v153
	v_fmamk_f32 v145, v145, 0x3a800000, v171
	v_cmp_gt_f32_e32 vcc, s9, v145
	v_mul_f32_e32 v153, 0x4b800000, v145
	s_nop 0
	v_cndmask_b32_e32 v145, v145, v153, vcc
	v_rsq_f32_e32 v145, v145
	s_nop 0
	v_mul_f32_e32 v153, 0x45800000, v145
	v_cndmask_b32_e32 v154, v145, v153, vcc
	v_pk_mul_f32 v[124:125], v[124:125], v[154:155] op_sel_hi:[1,0]
	v_pk_mul_f32 v[156:157], v[114:115], v[154:155] op_sel_hi:[1,0]
	v_pk_mul_f32 v[114:115], v[112:113], v[154:155] op_sel_hi:[1,0]
	v_mul_f32_e32 v112, 0xbfb8aa3b, v124
	v_mul_f32_e32 v113, 0xbfb8aa3b, v125
	v_exp_f32_e32 v112, v112
	v_exp_f32_e32 v113, v113
	v_pk_mul_f32 v[116:117], v[116:117], v[154:155] op_sel_hi:[1,0]
	v_pk_mul_f32 v[126:127], v[126:127], v[154:155] op_sel_hi:[1,0]
	v_add_f32_e32 v112, 1.0, v112
	v_add_f32_e32 v113, 1.0, v113
	v_rcp_f32_e32 v112, v112
	v_rcp_f32_e32 v113, v113
	v_pk_mul_f32 v[118:119], v[118:119], v[154:155] op_sel_hi:[1,0]
	v_pk_mul_f32 v[120:121], v[120:121], v[154:155] op_sel_hi:[1,0]
	v_mul_f32_e32 v112, v124, v112
	v_mul_f32_e32 v113, v125, v113
	v_mul_f32_e32 v112, v116, v112
	v_mul_f32_e32 v113, v117, v113
	v_cvt_pk_bf16_f32 v112, v112, v113
	v_mul_f32_e32 v113, 0xbfb8aa3b, v126
	v_mul_f32_e32 v116, 0xbfb8aa3b, v127
	v_exp_f32_e32 v113, v113
	v_exp_f32_e32 v116, v116
	v_pk_mul_f32 v[122:123], v[122:123], v[154:155] op_sel_hi:[1,0]
	v_add_f32_e32 v113, 1.0, v113
	v_add_f32_e32 v116, 1.0, v116
	v_rcp_f32_e32 v113, v113
	v_rcp_f32_e32 v116, v116
	v_mul_f32_e32 v113, v126, v113
	v_mul_f32_e32 v116, v127, v116
	v_mul_f32_e32 v113, v118, v113
	v_mul_f32_e32 v116, v119, v116
	v_cvt_pk_bf16_f32 v113, v113, v116
	v_mul_f32_e32 v116, 0xbfb8aa3b, v120
	v_exp_f32_e32 v116, v116
	v_lshlrev_b64 v[118:119], 1, v[146:147]
	v_add_f32_e32 v116, 1.0, v116
	v_rcp_f32_e32 v116, v116
	s_nop 0
	v_mul_f32_e32 v116, v120, v116
	v_mul_f32_e32 v114, v114, v116
	v_mul_f32_e32 v116, 0xbfb8aa3b, v121
	v_exp_f32_e32 v116, v116
	s_nop 0
	v_add_f32_e32 v116, 1.0, v116
	v_rcp_f32_e32 v116, v116
	s_nop 0
	v_mul_f32_e32 v116, v121, v116
	v_mul_f32_e32 v115, v115, v116
	v_cvt_pk_bf16_f32 v114, v114, v115
	v_mul_f32_e32 v115, 0xbfb8aa3b, v122
	v_mul_f32_e32 v116, 0xbfb8aa3b, v123
	v_exp_f32_e32 v115, v115
	v_exp_f32_e32 v116, v116
	v_add_f32_e32 v115, 1.0, v115
	v_add_f32_e32 v116, 1.0, v116
	v_rcp_f32_e32 v115, v115
	v_rcp_f32_e32 v116, v116
	v_mul_f32_e32 v115, v122, v115
	v_mul_f32_e32 v116, v123, v116
	v_mul_f32_e32 v115, v156, v115
	v_mul_f32_e32 v116, v157, v116
	v_cvt_pk_bf16_f32 v115, v115, v116
	v_mov_b64_e32 v[116:117], s[34:35]
	v_mad_i64_i32 v[120:121], s[0:1], v144, s11, v[116:117]
	v_lshl_add_u64 v[120:121], v[120:121], 0, v[118:119]
	global_store_dwordx4 v[120:121], v[112:115], off
	s_nop 1
	v_or_b32_e32 v112, 16, v144
	v_ashrrev_i32_e32 v113, 31, v112
	v_lshlrev_b64 v[114:115], 6, v[112:113]
	v_lshl_add_u64 v[114:115], v[138:139], 0, v[114:115]
	v_mov_b64_e32 v[120:121], v[204:205]
	v_mov_b64_e32 v[122:123], v[206:207]
	v_mov_b32_e32 v114, v121
	v_mov_b32_e32 v115, v122
	v_mov_b32_e32 v121, v123
	v_pk_add_f32 v[114:115], v[114:115], v[120:121]
	s_nop 0
	v_add_f32_e32 v113, v114, v115
	ds_bpermute_b32 v114, v151, v113
	s_waitcnt lgkmcnt(0)
; __device__ __forceinline__ unsigned pk2(float lo, float hi) { return pg8::cvt_pk_bf16(lo, hi); }
; __device__ __forceinline__ float siluf(float x) { return x * sigm(x); }
;     __device__ __forceinline__ void operator()(const pg8::f32x4 (&acc)[2][2][4][2], const pg8::Unit& u, int wr, int wc, int fr, int fq) const {
;         const int row0 = u.pm * 256 + wr * 64 + fr, col0 = u.pn * 128 + wc * 32 + 8 * fq;
; #pragma unroll
;         for (int ai = 0; ai < 2; ++ai)
; #pragma unroll
;             for (int m = 0; m < 4; ++m) {
;                 const size_t row = (size_t)(row0 + ai * 128 + m * 16);
;                 const float rs = row_rs4(ssq, row, fq);
;                 const pg8::f32x4 g0 = acc[ai][0][m][0] * rs, g1 = acc[ai][0][m][1] * rs, u0 = acc[ai][1][m][0] * rs, u1 = acc[ai][1][m][1] * rs;
;                 u32x4 w;
;                 w.x = pk2(siluf(g0[0]) * u0[0], siluf(g0[1]) * u0[1]); w.y = pk2(siluf(g0[2]) * u0[2], siluf(g0[3]) * u0[3]);
;                 w.z = pk2(siluf(g1[0]) * u1[0], siluf(g1[1]) * u1[1]); w.w = pk2(siluf(g1[2]) * u1[2], siluf(g1[3]) * u1[3]);
;                 *(u32x4*)(H + row * DFF + col0) = w;
;                 if (m == 3) asm volatile("" ::: "memory");
;             }
	v_add_f32_e32 v113, v113, v114
	ds_bpermute_b32 v114, v152, v113
	s_waitcnt lgkmcnt(0)
	v_add_f32_e32 v113, v113, v114
	v_fmamk_f32 v113, v113, 0x3a800000, v171
	v_cmp_gt_f32_e32 vcc, s9, v113
	v_mul_f32_e32 v114, 0x4b800000, v113
	s_nop 0
	v_cndmask_b32_e32 v113, v113, v114, vcc
	v_rsq_f32_e32 v113, v113
	s_nop 0
	v_mul_f32_e32 v114, 0x45800000, v113
	v_cndmask_b32_e32 v114, v113, v114, vcc
	v_pk_mul_f32 v[108:109], v[108:109], v[114:115] op_sel_hi:[1,0]
	v_pk_mul_f32 v[120:121], v[98:99], v[114:115] op_sel_hi:[1,0]
	v_pk_mul_f32 v[98:99], v[96:97], v[114:115] op_sel_hi:[1,0]
	v_mul_f32_e32 v96, 0xbfb8aa3b, v108
	v_mul_f32_e32 v97, 0xbfb8aa3b, v109
	v_exp_f32_e32 v96, v96
	v_exp_f32_e32 v97, v97
	v_pk_mul_f32 v[100:101], v[100:101], v[114:115] op_sel_hi:[1,0]
	v_pk_mul_f32 v[110:111], v[110:111], v[114:115] op_sel_hi:[1,0]
	v_add_f32_e32 v96, 1.0, v96
	v_add_f32_e32 v97, 1.0, v97
	v_rcp_f32_e32 v96, v96
	v_rcp_f32_e32 v97, v97
	v_pk_mul_f32 v[102:103], v[102:103], v[114:115] op_sel_hi:[1,0]
	v_pk_mul_f32 v[104:105], v[104:105], v[114:115] op_sel_hi:[1,0]
	v_mul_f32_e32 v96, v108, v96
	v_mul_f32_e32 v97, v109, v97
	v_mul_f32_e32 v96, v100, v96
	v_mul_f32_e32 v97, v101, v97
	v_cvt_pk_bf16_f32 v96, v96, v97
	v_mul_f32_e32 v97, 0xbfb8aa3b, v110
	v_mul_f32_e32 v100, 0xbfb8aa3b, v111
	v_exp_f32_e32 v97, v97
	v_exp_f32_e32 v100, v100
	v_pk_mul_f32 v[106:107], v[106:107], v[114:115] op_sel_hi:[1,0]
	v_add_f32_e32 v97, 1.0, v97
	v_add_f32_e32 v100, 1.0, v100
	v_rcp_f32_e32 v97, v97
	v_rcp_f32_e32 v100, v100
	v_mul_f32_e32 v97, v110, v97
	v_mul_f32_e32 v100, v111, v100
	v_mul_f32_e32 v97, v102, v97
	v_mul_f32_e32 v100, v103, v100
	v_cvt_pk_bf16_f32 v97, v97, v100
	v_mul_f32_e32 v100, 0xbfb8aa3b, v104
	v_exp_f32_e32 v100, v100
	s_nop 0
	v_add_f32_e32 v100, 1.0, v100
	v_rcp_f32_e32 v100, v100
	s_nop 0
	v_mul_f32_e32 v100, v104, v100
	v_mul_f32_e32 v98, v98, v100
	v_mul_f32_e32 v100, 0xbfb8aa3b, v105
	v_exp_f32_e32 v100, v100
	s_nop 0
	v_add_f32_e32 v100, 1.0, v100
	v_rcp_f32_e32 v100, v100
	s_nop 0
	v_mul_f32_e32 v100, v105, v100
	v_mul_f32_e32 v99, v99, v100
	v_cvt_pk_bf16_f32 v98, v98, v99
	v_mul_f32_e32 v99, 0xbfb8aa3b, v106
	v_mul_f32_e32 v100, 0xbfb8aa3b, v107
	v_exp_f32_e32 v99, v99
	v_exp_f32_e32 v100, v100
	v_add_f32_e32 v99, 1.0, v99
	v_add_f32_e32 v100, 1.0, v100
	v_rcp_f32_e32 v99, v99
	v_rcp_f32_e32 v100, v100
	v_mul_f32_e32 v99, v106, v99
	v_mul_f32_e32 v100, v107, v100
	v_mul_f32_e32 v99, v120, v99
	v_mul_f32_e32 v100, v121, v100
	v_cvt_pk_bf16_f32 v99, v99, v100
	v_mad_i64_i32 v[100:101], s[0:1], v112, s11, v[116:117]
	v_lshl_add_u64 v[100:101], v[100:101], 0, v[118:119]
	global_store_dwordx4 v[100:101], v[96:99], off
	s_nop 1
	v_or_b32_e32 v96, 32, v144
	v_ashrrev_i32_e32 v97, 31, v96
	v_lshlrev_b64 v[98:99], 6, v[96:97]
	v_lshl_add_u64 v[98:99], v[138:139], 0, v[98:99]
	v_mov_b64_e32 v[98:99], v[208:209]
	v_mov_b64_e32 v[100:101], v[210:211]
	v_mov_b32_e32 v102, v99
	v_mov_b32_e32 v103, v100
	v_mov_b32_e32 v99, v101
	v_pk_add_f32 v[98:99], v[102:103], v[98:99]
	s_nop 0
	v_add_f32_e32 v97, v98, v99
	ds_bpermute_b32 v98, v151, v97
	s_waitcnt lgkmcnt(0)
	v_add_f32_e32 v97, v97, v98
	ds_bpermute_b32 v98, v152, v97
	s_waitcnt lgkmcnt(0)
	v_add_f32_e32 v97, v97, v98
	v_fmamk_f32 v97, v97, 0x3a800000, v171
	v_cmp_gt_f32_e32 vcc, s9, v97
	v_mul_f32_e32 v98, 0x4b800000, v97
	s_nop 0
	v_cndmask_b32_e32 v97, v97, v98, vcc
	v_rsq_f32_e32 v97, v97
	s_nop 0
	v_mul_f32_e32 v98, 0x45800000, v97
	v_cndmask_b32_e32 v98, v97, v98, vcc
	v_pk_mul_f32 v[92:93], v[92:93], v[98:99] op_sel_hi:[1,0]
	v_pk_mul_f32 v[100:101], v[82:83], v[98:99] op_sel_hi:[1,0]
	v_pk_mul_f32 v[82:83], v[80:81], v[98:99] op_sel_hi:[1,0]
	v_mul_f32_e32 v80, 0xbfb8aa3b, v92
	v_mul_f32_e32 v81, 0xbfb8aa3b, v93
	v_exp_f32_e32 v80, v80
	v_exp_f32_e32 v81, v81
	v_pk_mul_f32 v[84:85], v[84:85], v[98:99] op_sel_hi:[1,0]
	v_pk_mul_f32 v[94:95], v[94:95], v[98:99] op_sel_hi:[1,0]
	v_add_f32_e32 v80, 1.0, v80
	v_add_f32_e32 v81, 1.0, v81
	v_rcp_f32_e32 v80, v80
	v_rcp_f32_e32 v81, v81
	v_pk_mul_f32 v[86:87], v[86:87], v[98:99] op_sel_hi:[1,0]
	v_pk_mul_f32 v[88:89], v[88:89], v[98:99] op_sel_hi:[1,0]
	v_mul_f32_e32 v80, v92, v80
	v_mul_f32_e32 v81, v93, v81
	v_mul_f32_e32 v80, v84, v80
	v_mul_f32_e32 v81, v85, v81
	v_cvt_pk_bf16_f32 v80, v80, v81
	v_mul_f32_e32 v81, 0xbfb8aa3b, v94
	v_mul_f32_e32 v84, 0xbfb8aa3b, v95
	v_exp_f32_e32 v81, v81
	v_exp_f32_e32 v84, v84
	v_pk_mul_f32 v[90:91], v[90:91], v[98:99] op_sel_hi:[1,0]
	v_add_f32_e32 v81, 1.0, v81
	v_add_f32_e32 v84, 1.0, v84
	v_rcp_f32_e32 v81, v81
	v_rcp_f32_e32 v84, v84
	v_mul_f32_e32 v81, v94, v81
	v_mul_f32_e32 v84, v95, v84
	v_mul_f32_e32 v81, v86, v81
	v_mul_f32_e32 v84, v87, v84
	v_cvt_pk_bf16_f32 v81, v81, v84
	v_mul_f32_e32 v84, 0xbfb8aa3b, v88
	v_exp_f32_e32 v84, v84
	s_nop 0
	v_add_f32_e32 v84, 1.0, v84
	v_rcp_f32_e32 v84, v84
	s_nop 0
	v_mul_f32_e32 v84, v88, v84
	v_mul_f32_e32 v82, v82, v84
	v_mul_f32_e32 v84, 0xbfb8aa3b, v89
	v_exp_f32_e32 v84, v84
	s_nop 0
	v_add_f32_e32 v84, 1.0, v84
	v_rcp_f32_e32 v84, v84
	s_nop 0
	v_mul_f32_e32 v84, v89, v84
	v_mul_f32_e32 v83, v83, v84
	v_cvt_pk_bf16_f32 v82, v82, v83
	v_mul_f32_e32 v83, 0xbfb8aa3b, v90
	v_mul_f32_e32 v84, 0xbfb8aa3b, v91
	v_exp_f32_e32 v83, v83
	v_exp_f32_e32 v84, v84
	v_add_f32_e32 v83, 1.0, v83
	v_add_f32_e32 v84, 1.0, v84
	v_rcp_f32_e32 v83, v83
	v_rcp_f32_e32 v84, v84
	v_mul_f32_e32 v83, v90, v83
	v_mul_f32_e32 v84, v91, v84
	v_mul_f32_e32 v83, v100, v83
	v_mul_f32_e32 v84, v101, v84
	v_cvt_pk_bf16_f32 v83, v83, v84
	v_mad_i64_i32 v[84:85], s[0:1], v96, s11, v[116:117]
	v_lshl_add_u64 v[84:85], v[84:85], 0, v[118:119]
	global_store_dwordx4 v[84:85], v[80:83], off
	s_nop 1
	v_or_b32_e32 v80, 48, v144
	v_ashrrev_i32_e32 v81, 31, v80
	v_lshlrev_b64 v[82:83], 6, v[80:81]
	v_lshl_add_u64 v[82:83], v[138:139], 0, v[82:83]
	v_mov_b64_e32 v[82:83], v[212:213]
	v_mov_b64_e32 v[84:85], v[214:215]
	v_mov_b32_e32 v86, v83
	v_mov_b32_e32 v87, v84
	v_mov_b32_e32 v83, v85
	v_pk_add_f32 v[82:83], v[86:87], v[82:83]
	s_nop 0
	v_add_f32_e32 v81, v82, v83
	ds_bpermute_b32 v82, v151, v81
	s_waitcnt lgkmcnt(0)
; __device__ __forceinline__ unsigned pk2(float lo, float hi) { return pg8::cvt_pk_bf16(lo, hi); }
; __device__ __forceinline__ float siluf(float x) { return x * sigm(x); }
;     __device__ __forceinline__ void operator()(const pg8::f32x4 (&acc)[2][2][4][2], const pg8::Unit& u, int wr, int wc, int fr, int fq) const {
;         const int row0 = u.pm * 256 + wr * 64 + fr, col0 = u.pn * 128 + wc * 32 + 8 * fq;
; #pragma unroll
;         for (int ai = 0; ai < 2; ++ai)
; #pragma unroll
;             for (int m = 0; m < 4; ++m) {
;                 const size_t row = (size_t)(row0 + ai * 128 + m * 16);
;                 const float rs = row_rs4(ssq, row, fq);
;                 const pg8::f32x4 g0 = acc[ai][0][m][0] * rs, g1 = acc[ai][0][m][1] * rs, u0 = acc[ai][1][m][0] * rs, u1 = acc[ai][1][m][1] * rs;
;                 u32x4 w;
;                 w.x = pk2(siluf(g0[0]) * u0[0], siluf(g0[1]) * u0[1]); w.y = pk2(siluf(g0[2]) * u0[2], siluf(g0[3]) * u0[3]);
;                 w.z = pk2(siluf(g1[0]) * u1[0], siluf(g1[1]) * u1[1]); w.w = pk2(siluf(g1[2]) * u1[2], siluf(g1[3]) * u1[3]);
;                 *(u32x4*)(H + row * DFF + col0) = w;
;                 if (m == 3) asm volatile("" ::: "memory");
;             }
	v_add_f32_e32 v81, v81, v82
	ds_bpermute_b32 v82, v152, v81
	s_waitcnt lgkmcnt(0)
	v_add_f32_e32 v81, v81, v82
	v_fmamk_f32 v81, v81, 0x3a800000, v171
	v_cmp_gt_f32_e32 vcc, s9, v81
	v_mul_f32_e32 v82, 0x4b800000, v81
	s_nop 0
	v_cndmask_b32_e32 v81, v81, v82, vcc
	v_rsq_f32_e32 v81, v81
	s_nop 0
	v_mul_f32_e32 v82, 0x45800000, v81
	v_cndmask_b32_e32 v82, v81, v82, vcc
	v_pk_mul_f32 v[76:77], v[76:77], v[82:83] op_sel_hi:[1,0]
	v_pk_mul_f32 v[84:85], v[66:67], v[82:83] op_sel_hi:[1,0]
	v_pk_mul_f32 v[66:67], v[64:65], v[82:83] op_sel_hi:[1,0]
	v_mul_f32_e32 v64, 0xbfb8aa3b, v76
	v_mul_f32_e32 v65, 0xbfb8aa3b, v77
	v_exp_f32_e32 v64, v64
	v_exp_f32_e32 v65, v65
	v_pk_mul_f32 v[68:69], v[68:69], v[82:83] op_sel_hi:[1,0]
	v_pk_mul_f32 v[78:79], v[78:79], v[82:83] op_sel_hi:[1,0]
	v_add_f32_e32 v64, 1.0, v64
	v_add_f32_e32 v65, 1.0, v65
	v_rcp_f32_e32 v64, v64
	v_rcp_f32_e32 v65, v65
	v_pk_mul_f32 v[70:71], v[70:71], v[82:83] op_sel_hi:[1,0]
	v_pk_mul_f32 v[72:73], v[72:73], v[82:83] op_sel_hi:[1,0]
	v_mul_f32_e32 v64, v76, v64
	v_mul_f32_e32 v65, v77, v65
	v_mul_f32_e32 v64, v68, v64
	v_mul_f32_e32 v65, v69, v65
	v_cvt_pk_bf16_f32 v64, v64, v65
	v_mul_f32_e32 v65, 0xbfb8aa3b, v78
	v_mul_f32_e32 v68, 0xbfb8aa3b, v79
	v_exp_f32_e32 v65, v65
	v_exp_f32_e32 v68, v68
	v_pk_mul_f32 v[74:75], v[74:75], v[82:83] op_sel_hi:[1,0]
	v_add_f32_e32 v65, 1.0, v65
	v_add_f32_e32 v68, 1.0, v68
	v_rcp_f32_e32 v65, v65
	v_rcp_f32_e32 v68, v68
	v_mul_f32_e32 v65, v78, v65
	v_mul_f32_e32 v68, v79, v68
	v_mul_f32_e32 v65, v70, v65
	v_mul_f32_e32 v68, v71, v68
	v_cvt_pk_bf16_f32 v65, v65, v68
	v_mul_f32_e32 v68, 0xbfb8aa3b, v72
	v_exp_f32_e32 v68, v68
	s_nop 0
	v_add_f32_e32 v68, 1.0, v68
	v_rcp_f32_e32 v68, v68
	s_nop 0
	v_mul_f32_e32 v68, v72, v68
	v_mul_f32_e32 v66, v66, v68
	v_mul_f32_e32 v68, 0xbfb8aa3b, v73
	v_exp_f32_e32 v68, v68
	s_nop 0
	v_add_f32_e32 v68, 1.0, v68
	v_rcp_f32_e32 v68, v68
	s_nop 0
	v_mul_f32_e32 v68, v73, v68
	v_mul_f32_e32 v67, v67, v68
	v_cvt_pk_bf16_f32 v66, v66, v67
	v_mul_f32_e32 v67, 0xbfb8aa3b, v74
	v_mul_f32_e32 v68, 0xbfb8aa3b, v75
	v_exp_f32_e32 v67, v67
	v_exp_f32_e32 v68, v68
	v_add_f32_e32 v67, 1.0, v67
	v_add_f32_e32 v68, 1.0, v68
	v_rcp_f32_e32 v67, v67
	v_rcp_f32_e32 v68, v68
	v_mul_f32_e32 v67, v74, v67
	v_mul_f32_e32 v68, v75, v68
	v_mul_f32_e32 v67, v84, v67
	v_mul_f32_e32 v68, v85, v68
	v_cvt_pk_bf16_f32 v67, v67, v68
	v_mad_i64_i32 v[68:69], s[0:1], v80, s11, v[116:117]
	v_lshl_add_u64 v[68:69], v[68:69], 0, v[118:119]
	global_store_dwordx4 v[68:69], v[64:67], off
	s_nop 1
	v_add_u32_e32 v64, 0x80, v144
	v_ashrrev_i32_e32 v65, 31, v64
	v_lshlrev_b64 v[66:67], 6, v[64:65]
	v_lshl_add_u64 v[66:67], v[138:139], 0, v[66:67]
	v_mov_b64_e32 v[66:67], v[216:217]
	v_mov_b64_e32 v[68:69], v[218:219]
	v_mov_b32_e32 v70, v67
	v_mov_b32_e32 v71, v68
	v_mov_b32_e32 v67, v69
	v_pk_add_f32 v[66:67], v[70:71], v[66:67]
	s_nop 0
	v_add_f32_e32 v65, v66, v67
	ds_bpermute_b32 v66, v151, v65
	s_waitcnt lgkmcnt(0)
	v_add_f32_e32 v65, v65, v66
	ds_bpermute_b32 v66, v152, v65
	s_waitcnt lgkmcnt(0)
	v_add_f32_e32 v65, v65, v66
	v_fmamk_f32 v65, v65, 0x3a800000, v171
	v_cmp_gt_f32_e32 vcc, s9, v65
	v_mul_f32_e32 v66, 0x4b800000, v65
	s_nop 0
	v_cndmask_b32_e32 v65, v65, v66, vcc
	v_rsq_f32_e32 v65, v65
	s_nop 0
	v_mul_f32_e32 v66, 0x45800000, v65
	v_cndmask_b32_e32 v66, v65, v66, vcc
	v_pk_mul_f32 v[60:61], v[60:61], v[66:67] op_sel_hi:[1,0]
	v_pk_mul_f32 v[68:69], v[50:51], v[66:67] op_sel_hi:[1,0]
	v_pk_mul_f32 v[50:51], v[48:49], v[66:67] op_sel_hi:[1,0]
	v_mul_f32_e32 v48, 0xbfb8aa3b, v60
	v_mul_f32_e32 v49, 0xbfb8aa3b, v61
	v_exp_f32_e32 v48, v48
	v_exp_f32_e32 v49, v49
	v_pk_mul_f32 v[52:53], v[52:53], v[66:67] op_sel_hi:[1,0]
	v_pk_mul_f32 v[62:63], v[62:63], v[66:67] op_sel_hi:[1,0]
	v_add_f32_e32 v48, 1.0, v48
	v_add_f32_e32 v49, 1.0, v49
	v_rcp_f32_e32 v48, v48
	v_rcp_f32_e32 v49, v49
	v_pk_mul_f32 v[54:55], v[54:55], v[66:67] op_sel_hi:[1,0]
	v_pk_mul_f32 v[56:57], v[56:57], v[66:67] op_sel_hi:[1,0]
	v_mul_f32_e32 v48, v60, v48
	v_mul_f32_e32 v49, v61, v49
	v_mul_f32_e32 v48, v52, v48
	v_mul_f32_e32 v49, v53, v49
	v_cvt_pk_bf16_f32 v48, v48, v49
	v_mul_f32_e32 v49, 0xbfb8aa3b, v62
	v_mul_f32_e32 v52, 0xbfb8aa3b, v63
	v_exp_f32_e32 v49, v49
	v_exp_f32_e32 v52, v52
	v_pk_mul_f32 v[58:59], v[58:59], v[66:67] op_sel_hi:[1,0]
	v_add_f32_e32 v49, 1.0, v49
	v_add_f32_e32 v52, 1.0, v52
	v_rcp_f32_e32 v49, v49
	v_rcp_f32_e32 v52, v52
	v_mul_f32_e32 v49, v62, v49
	v_mul_f32_e32 v52, v63, v52
	v_mul_f32_e32 v49, v54, v49
	v_mul_f32_e32 v52, v55, v52
	v_cvt_pk_bf16_f32 v49, v49, v52
	v_mul_f32_e32 v52, 0xbfb8aa3b, v56
	v_exp_f32_e32 v52, v52
	s_nop 0
	v_add_f32_e32 v52, 1.0, v52
	v_rcp_f32_e32 v52, v52
	s_nop 0
	v_mul_f32_e32 v52, v56, v52
	v_mul_f32_e32 v50, v50, v52
	v_mul_f32_e32 v52, 0xbfb8aa3b, v57
	v_exp_f32_e32 v52, v52
	s_nop 0
	v_add_f32_e32 v52, 1.0, v52
	v_rcp_f32_e32 v52, v52
	s_nop 0
	v_mul_f32_e32 v52, v57, v52
	v_mul_f32_e32 v51, v51, v52
	v_cvt_pk_bf16_f32 v50, v50, v51
	v_mul_f32_e32 v51, 0xbfb8aa3b, v58
	v_mul_f32_e32 v52, 0xbfb8aa3b, v59
	v_exp_f32_e32 v51, v51
	v_exp_f32_e32 v52, v52
	v_add_f32_e32 v51, 1.0, v51
	v_add_f32_e32 v52, 1.0, v52
	v_rcp_f32_e32 v51, v51
	v_rcp_f32_e32 v52, v52
	v_mul_f32_e32 v51, v58, v51
	v_mul_f32_e32 v52, v59, v52
	v_mul_f32_e32 v51, v68, v51
	v_mul_f32_e32 v52, v69, v52
	v_cvt_pk_bf16_f32 v51, v51, v52
	v_mad_i64_i32 v[52:53], s[0:1], v64, s11, v[116:117]
	v_lshl_add_u64 v[52:53], v[52:53], 0, v[118:119]
	global_store_dwordx4 v[52:53], v[48:51], off
	s_nop 1
	v_add_u32_e32 v48, 0x90, v144
	v_ashrrev_i32_e32 v49, 31, v48
	v_lshlrev_b64 v[50:51], 6, v[48:49]
	v_lshl_add_u64 v[50:51], v[138:139], 0, v[50:51]
	v_mov_b64_e32 v[50:51], v[220:221]
	v_mov_b64_e32 v[52:53], v[222:223]
	v_mov_b32_e32 v54, v51
	v_mov_b32_e32 v55, v52
	v_mov_b32_e32 v51, v53
	v_pk_add_f32 v[50:51], v[54:55], v[50:51]
	s_nop 0
	v_add_f32_e32 v49, v50, v51
	ds_bpermute_b32 v50, v151, v49
	s_waitcnt lgkmcnt(0)
; __device__ __forceinline__ unsigned pk2(float lo, float hi) { return pg8::cvt_pk_bf16(lo, hi); }
; __device__ __forceinline__ float siluf(float x) { return x * sigm(x); }
;     __device__ __forceinline__ void operator()(const pg8::f32x4 (&acc)[2][2][4][2], const pg8::Unit& u, int wr, int wc, int fr, int fq) const {
;         const int row0 = u.pm * 256 + wr * 64 + fr, col0 = u.pn * 128 + wc * 32 + 8 * fq;
; #pragma unroll
;         for (int ai = 0; ai < 2; ++ai)
; #pragma unroll
;             for (int m = 0; m < 4; ++m) {
;                 const size_t row = (size_t)(row0 + ai * 128 + m * 16);
;                 const float rs = row_rs4(ssq, row, fq);
;                 const pg8::f32x4 g0 = acc[ai][0][m][0] * rs, g1 = acc[ai][0][m][1] * rs, u0 = acc[ai][1][m][0] * rs, u1 = acc[ai][1][m][1] * rs;
;                 u32x4 w;
;                 w.x = pk2(siluf(g0[0]) * u0[0], siluf(g0[1]) * u0[1]); w.y = pk2(siluf(g0[2]) * u0[2], siluf(g0[3]) * u0[3]);
;                 w.z = pk2(siluf(g1[0]) * u1[0], siluf(g1[1]) * u1[1]); w.w = pk2(siluf(g1[2]) * u1[2], siluf(g1[3]) * u1[3]);
;                 *(u32x4*)(H + row * DFF + col0) = w;
;                 if (m == 3) asm volatile("" ::: "memory");
;             }
	v_add_f32_e32 v49, v49, v50
	ds_bpermute_b32 v50, v152, v49
	s_waitcnt lgkmcnt(0)
	v_add_f32_e32 v49, v49, v50
	v_fmamk_f32 v49, v49, 0x3a800000, v171
	v_cmp_gt_f32_e32 vcc, s9, v49
	v_mul_f32_e32 v50, 0x4b800000, v49
	s_nop 0
	v_cndmask_b32_e32 v49, v49, v50, vcc
	v_rsq_f32_e32 v49, v49
	s_nop 0
	v_mul_f32_e32 v50, 0x45800000, v49
	v_cndmask_b32_e32 v50, v49, v50, vcc
	v_pk_mul_f32 v[44:45], v[44:45], v[50:51] op_sel_hi:[1,0]
	v_pk_mul_f32 v[52:53], v[34:35], v[50:51] op_sel_hi:[1,0]
	v_pk_mul_f32 v[34:35], v[32:33], v[50:51] op_sel_hi:[1,0]
	v_mul_f32_e32 v32, 0xbfb8aa3b, v44
	v_mul_f32_e32 v33, 0xbfb8aa3b, v45
	v_exp_f32_e32 v32, v32
	v_exp_f32_e32 v33, v33
	v_pk_mul_f32 v[36:37], v[36:37], v[50:51] op_sel_hi:[1,0]
	v_pk_mul_f32 v[46:47], v[46:47], v[50:51] op_sel_hi:[1,0]
	v_add_f32_e32 v32, 1.0, v32
	v_add_f32_e32 v33, 1.0, v33
	v_rcp_f32_e32 v32, v32
	v_rcp_f32_e32 v33, v33
	v_pk_mul_f32 v[38:39], v[38:39], v[50:51] op_sel_hi:[1,0]
	v_pk_mul_f32 v[40:41], v[40:41], v[50:51] op_sel_hi:[1,0]
	v_mul_f32_e32 v32, v44, v32
	v_mul_f32_e32 v33, v45, v33
	v_mul_f32_e32 v32, v36, v32
	v_mul_f32_e32 v33, v37, v33
	v_cvt_pk_bf16_f32 v32, v32, v33
	v_mul_f32_e32 v33, 0xbfb8aa3b, v46
	v_mul_f32_e32 v36, 0xbfb8aa3b, v47
	v_exp_f32_e32 v33, v33
	v_exp_f32_e32 v36, v36
	v_pk_mul_f32 v[42:43], v[42:43], v[50:51] op_sel_hi:[1,0]
	v_add_f32_e32 v33, 1.0, v33
	v_add_f32_e32 v36, 1.0, v36
	v_rcp_f32_e32 v33, v33
	v_rcp_f32_e32 v36, v36
	v_mul_f32_e32 v33, v46, v33
	v_mul_f32_e32 v36, v47, v36
	v_mul_f32_e32 v33, v38, v33
	v_mul_f32_e32 v36, v39, v36
	v_cvt_pk_bf16_f32 v33, v33, v36
	v_mul_f32_e32 v36, 0xbfb8aa3b, v40
	v_exp_f32_e32 v36, v36
	s_nop 0
	v_add_f32_e32 v36, 1.0, v36
	v_rcp_f32_e32 v36, v36
	s_nop 0
	v_mul_f32_e32 v36, v40, v36
	v_mul_f32_e32 v34, v34, v36
	v_mul_f32_e32 v36, 0xbfb8aa3b, v41
	v_exp_f32_e32 v36, v36
	s_nop 0
	v_add_f32_e32 v36, 1.0, v36
	v_rcp_f32_e32 v36, v36
	s_nop 0
	v_mul_f32_e32 v36, v41, v36
	v_mul_f32_e32 v35, v35, v36
	v_cvt_pk_bf16_f32 v34, v34, v35
	v_mul_f32_e32 v35, 0xbfb8aa3b, v42
	v_mul_f32_e32 v36, 0xbfb8aa3b, v43
	v_exp_f32_e32 v35, v35
	v_exp_f32_e32 v36, v36
	v_add_f32_e32 v35, 1.0, v35
	v_add_f32_e32 v36, 1.0, v36
	v_rcp_f32_e32 v35, v35
	v_rcp_f32_e32 v36, v36
	v_mul_f32_e32 v35, v42, v35
	v_mul_f32_e32 v36, v43, v36
	v_mul_f32_e32 v35, v52, v35
	v_mul_f32_e32 v36, v53, v36
	v_cvt_pk_bf16_f32 v35, v35, v36
	v_mad_i64_i32 v[36:37], s[0:1], v48, s11, v[116:117]
	v_lshl_add_u64 v[36:37], v[36:37], 0, v[118:119]
	global_store_dwordx4 v[36:37], v[32:35], off
	s_nop 1
	v_add_u32_e32 v32, 0xa0, v144
	v_ashrrev_i32_e32 v33, 31, v32
	v_lshlrev_b64 v[34:35], 6, v[32:33]
	v_lshl_add_u64 v[34:35], v[138:139], 0, v[34:35]
	v_mov_b64_e32 v[34:35], v[224:225]
	v_mov_b64_e32 v[36:37], v[226:227]
	v_mov_b32_e32 v38, v35
	v_mov_b32_e32 v39, v36
	v_mov_b32_e32 v35, v37
	v_pk_add_f32 v[34:35], v[38:39], v[34:35]
	s_nop 0
	v_add_f32_e32 v33, v34, v35
	ds_bpermute_b32 v34, v151, v33
	s_waitcnt lgkmcnt(0)
	v_add_f32_e32 v33, v33, v34
	ds_bpermute_b32 v34, v152, v33
	s_waitcnt lgkmcnt(0)
; #define PG8_BAR __builtin_amdgcn_s_barrier()
; __device__ __forceinline__ unsigned pk2(float lo, float hi) { return pg8::cvt_pk_bf16(lo, hi); }
; __device__ __forceinline__ float siluf(float x) { return x * sigm(x); }
; template <class Epi, class Sched, bool ALIGN_EPI = false, bool SP2 = false>
; __device__ __forceinline__ void gemm_phase(PG8_LAS unsigned char* lds, const Gemm g, const Sched& S, const Epi& E) {
;     ...
;         if constexpr (ALIGN_EPI) { if (wr == 0) PG8_BAR; }
;         if constexpr (!Epi::AFTER_DRAIN) { E(acc, cur, wr, wc, fr, fq); S.done(cur); }
;         if (!has_next) break;
; #pragma unroll
;         for (int a = 0; a < 2; ++a)
; #pragma unroll
;             for (int b = 0; b < 2; ++b)
; #pragma unroll
;                 for (int m = 0; m < 4; ++m)
; #pragma unroll
;                     for (int n = 0; n < 2; ++n) acc[a][b][m][n] = (f32x4){0.f, 0.f, 0.f, 0.f};
;         cur = nxt; cA = nA; cB = nB; ++ui;
;         if constexpr (ALIGN_EPI) { if (wr == 1) PG8_BAR; }
;     __device__ __forceinline__ void operator()(const pg8::f32x4 (&acc)[2][2][4][2], const pg8::Unit& u, int wr, int wc, int fr, int fq) const {
;         const int row0 = u.pm * 256 + wr * 64 + fr, col0 = u.pn * 128 + wc * 32 + 8 * fq;
; #pragma unroll
;         for (int ai = 0; ai < 2; ++ai)
; #pragma unroll
;             for (int m = 0; m < 4; ++m) {
;                 const size_t row = (size_t)(row0 + ai * 128 + m * 16);
;                 const float rs = row_rs4(ssq, row, fq);
;                 const pg8::f32x4 g0 = acc[ai][0][m][0] * rs, g1 = acc[ai][0][m][1] * rs, u0 = acc[ai][1][m][0] * rs, u1 = acc[ai][1][m][1] * rs;
;                 u32x4 w;
;                 w.x = pk2(siluf(g0[0]) * u0[0], siluf(g0[1]) * u0[1]); w.y = pk2(siluf(g0[2]) * u0[2], siluf(g0[3]) * u0[3]);
;                 w.z = pk2(siluf(g1[0]) * u1[0], siluf(g1[1]) * u1[1]); w.w = pk2(siluf(g1[2]) * u1[2], siluf(g1[3]) * u1[3]);
;                 *(u32x4*)(H + row * DFF + col0) = w;
;                 if (m == 3) asm volatile("" ::: "memory");
;             }
	v_add_f32_e32 v33, v33, v34
	v_fmamk_f32 v33, v33, 0x3a800000, v171
	v_cmp_gt_f32_e32 vcc, s9, v33
	v_mul_f32_e32 v34, 0x4b800000, v33
	s_nop 0
	v_cndmask_b32_e32 v33, v33, v34, vcc
	v_rsq_f32_e32 v33, v33
	s_nop 0
	v_mul_f32_e32 v34, 0x45800000, v33
	v_cndmask_b32_e32 v34, v33, v34, vcc
	v_pk_mul_f32 v[28:29], v[28:29], v[34:35] op_sel_hi:[1,0]
	v_pk_mul_f32 v[36:37], v[18:19], v[34:35] op_sel_hi:[1,0]
	v_pk_mul_f32 v[18:19], v[16:17], v[34:35] op_sel_hi:[1,0]
	v_mul_f32_e32 v16, 0xbfb8aa3b, v28
	v_mul_f32_e32 v17, 0xbfb8aa3b, v29
	v_exp_f32_e32 v16, v16
	v_exp_f32_e32 v17, v17
	v_pk_mul_f32 v[20:21], v[20:21], v[34:35] op_sel_hi:[1,0]
	v_pk_mul_f32 v[30:31], v[30:31], v[34:35] op_sel_hi:[1,0]
	v_add_f32_e32 v16, 1.0, v16
	v_add_f32_e32 v17, 1.0, v17
	v_rcp_f32_e32 v16, v16
	v_rcp_f32_e32 v17, v17
	v_pk_mul_f32 v[22:23], v[22:23], v[34:35] op_sel_hi:[1,0]
	v_pk_mul_f32 v[24:25], v[24:25], v[34:35] op_sel_hi:[1,0]
	v_mul_f32_e32 v16, v28, v16
	v_mul_f32_e32 v17, v29, v17
	v_mul_f32_e32 v16, v20, v16
	v_mul_f32_e32 v17, v21, v17
	v_cvt_pk_bf16_f32 v16, v16, v17
	v_mul_f32_e32 v17, 0xbfb8aa3b, v30
	v_mul_f32_e32 v20, 0xbfb8aa3b, v31
	v_exp_f32_e32 v17, v17
	v_exp_f32_e32 v20, v20
	v_pk_mul_f32 v[26:27], v[26:27], v[34:35] op_sel_hi:[1,0]
	v_add_f32_e32 v17, 1.0, v17
	v_add_f32_e32 v20, 1.0, v20
	v_rcp_f32_e32 v17, v17
	v_rcp_f32_e32 v20, v20
	v_mul_f32_e32 v17, v30, v17
	v_mul_f32_e32 v20, v31, v20
	v_mul_f32_e32 v17, v22, v17
	v_mul_f32_e32 v20, v23, v20
	v_cvt_pk_bf16_f32 v17, v17, v20
	v_mul_f32_e32 v20, 0xbfb8aa3b, v24
	v_exp_f32_e32 v20, v20
	s_nop 0
	v_add_f32_e32 v20, 1.0, v20
	v_rcp_f32_e32 v20, v20
	s_nop 0
	v_mul_f32_e32 v20, v24, v20
	v_mul_f32_e32 v18, v18, v20
	v_mul_f32_e32 v20, 0xbfb8aa3b, v25
	v_exp_f32_e32 v20, v20
	s_nop 0
	v_add_f32_e32 v20, 1.0, v20
	v_rcp_f32_e32 v20, v20
	s_nop 0
	v_mul_f32_e32 v20, v25, v20
	v_mul_f32_e32 v19, v19, v20
	v_cvt_pk_bf16_f32 v18, v18, v19
	v_mul_f32_e32 v19, 0xbfb8aa3b, v26
	v_mul_f32_e32 v20, 0xbfb8aa3b, v27
	v_exp_f32_e32 v19, v19
	v_exp_f32_e32 v20, v20
	v_add_f32_e32 v19, 1.0, v19
	v_add_f32_e32 v20, 1.0, v20
	v_rcp_f32_e32 v19, v19
	v_rcp_f32_e32 v20, v20
	v_mul_f32_e32 v19, v26, v19
	v_mul_f32_e32 v20, v27, v20
	v_mul_f32_e32 v19, v36, v19
	v_mul_f32_e32 v20, v37, v20
	v_cvt_pk_bf16_f32 v19, v19, v20
	v_mad_i64_i32 v[20:21], s[0:1], v32, s11, v[116:117]
	v_lshl_add_u64 v[20:21], v[20:21], 0, v[118:119]
	global_store_dwordx4 v[20:21], v[16:19], off
	s_nop 1
	v_add_u32_e32 v16, 0xb0, v144
	v_ashrrev_i32_e32 v17, 31, v16
	v_lshlrev_b64 v[18:19], 6, v[16:17]
	v_lshl_add_u64 v[18:19], v[138:139], 0, v[18:19]
	v_mov_b64_e32 v[18:19], v[228:229]
	v_mov_b64_e32 v[20:21], v[230:231]
	v_mov_b32_e32 v22, v19
	v_mov_b32_e32 v23, v20
	v_mov_b32_e32 v19, v21
	v_pk_add_f32 v[18:19], v[22:23], v[18:19]
	s_nop 0
	v_add_f32_e32 v17, v18, v19
	ds_bpermute_b32 v18, v151, v17
	s_waitcnt lgkmcnt(0)
	v_add_f32_e32 v17, v17, v18
	ds_bpermute_b32 v18, v152, v17
	s_waitcnt lgkmcnt(0)
	v_add_f32_e32 v17, v17, v18
	v_fmamk_f32 v17, v17, 0x3a800000, v171
	v_cmp_gt_f32_e32 vcc, s9, v17
	v_mul_f32_e32 v18, 0x4b800000, v17
	s_nop 0
	v_cndmask_b32_e32 v17, v17, v18, vcc
	v_rsq_f32_e32 v17, v17
	s_nop 0
	v_mul_f32_e32 v18, 0x45800000, v17
	v_cndmask_b32_e32 v18, v17, v18, vcc
	v_pk_mul_f32 v[12:13], v[12:13], v[18:19] op_sel_hi:[1,0]
	v_pk_mul_f32 v[20:21], v[2:3], v[18:19] op_sel_hi:[1,0]
	v_pk_mul_f32 v[2:3], v[0:1], v[18:19] op_sel_hi:[1,0]
	v_mul_f32_e32 v0, 0xbfb8aa3b, v12
	v_mul_f32_e32 v1, 0xbfb8aa3b, v13
	v_exp_f32_e32 v0, v0
	v_exp_f32_e32 v1, v1
	v_pk_mul_f32 v[4:5], v[4:5], v[18:19] op_sel_hi:[1,0]
	v_pk_mul_f32 v[14:15], v[14:15], v[18:19] op_sel_hi:[1,0]
	v_add_f32_e32 v0, 1.0, v0
	v_add_f32_e32 v1, 1.0, v1
	v_rcp_f32_e32 v0, v0
	v_rcp_f32_e32 v1, v1
	v_pk_mul_f32 v[6:7], v[6:7], v[18:19] op_sel_hi:[1,0]
	v_pk_mul_f32 v[8:9], v[8:9], v[18:19] op_sel_hi:[1,0]
	v_mul_f32_e32 v0, v12, v0
	v_mul_f32_e32 v1, v13, v1
	v_mul_f32_e32 v0, v4, v0
	v_mul_f32_e32 v1, v5, v1
	v_cvt_pk_bf16_f32 v0, v0, v1
	v_mul_f32_e32 v1, 0xbfb8aa3b, v14
	v_mul_f32_e32 v4, 0xbfb8aa3b, v15
	v_exp_f32_e32 v1, v1
	v_exp_f32_e32 v4, v4
	v_pk_mul_f32 v[10:11], v[10:11], v[18:19] op_sel_hi:[1,0]
	s_andn2_b64 vcc, exec, s[38:39]
	v_add_f32_e32 v1, 1.0, v1
	v_add_f32_e32 v4, 1.0, v4
	v_rcp_f32_e32 v1, v1
	v_rcp_f32_e32 v4, v4
	v_mul_f32_e32 v1, v14, v1
	v_mul_f32_e32 v4, v15, v4
	v_mul_f32_e32 v1, v6, v1
	v_mul_f32_e32 v4, v7, v4
	v_cvt_pk_bf16_f32 v1, v1, v4
	v_mul_f32_e32 v4, 0xbfb8aa3b, v8
	v_exp_f32_e32 v4, v4
	s_nop 0
	v_add_f32_e32 v4, 1.0, v4
	v_rcp_f32_e32 v4, v4
	s_nop 0
	v_mul_f32_e32 v4, v8, v4
	v_mul_f32_e32 v2, v2, v4
	v_mul_f32_e32 v4, 0xbfb8aa3b, v9
	v_exp_f32_e32 v4, v4
	s_nop 0
	v_add_f32_e32 v4, 1.0, v4
	v_rcp_f32_e32 v4, v4
	s_nop 0
	v_mul_f32_e32 v4, v9, v4
	v_mul_f32_e32 v3, v3, v4
	v_cvt_pk_bf16_f32 v2, v2, v3
	v_mul_f32_e32 v3, 0xbfb8aa3b, v10
	v_mul_f32_e32 v4, 0xbfb8aa3b, v11
	v_exp_f32_e32 v3, v3
	v_exp_f32_e32 v4, v4
	v_add_f32_e32 v3, 1.0, v3
	v_add_f32_e32 v4, 1.0, v4
	v_rcp_f32_e32 v3, v3
	v_rcp_f32_e32 v4, v4
	v_mul_f32_e32 v3, v10, v3
	v_mul_f32_e32 v4, v11, v4
	v_mul_f32_e32 v3, v20, v3
	v_mul_f32_e32 v4, v21, v4
	v_cvt_pk_bf16_f32 v3, v3, v4
	v_mad_i64_i32 v[4:5], s[0:1], v16, s11, v[116:117]
	v_lshl_add_u64 v[4:5], v[4:5], 0, v[118:119]
	global_store_dwordx4 v[4:5], v[0:3], off
	s_mov_b64 s[0:1], -1
	s_cbranch_vccnz .LBB0_153
	s_andn2_b64 vcc, exec, s[4:5]
	s_cbranch_vccnz .LBB0_152
	s_barrier
	s_branch .LBB0_152

; #define LAS __attribute__((address_space(3)))
; __device__ __forceinline__ float sigm(float x) { return __builtin_amdgcn_rcpf(1.0f + __expf(-x)); }
; #define MFMA16(a, b, c) __builtin_amdgcn_mfma_f32_16x16x32_bf16((a), (b), (c), 0, 0, 0)
; __device__ __forceinline__ void lru_item(LAS unsigned char* lds, const bf16* proj, bf16* yout, const float* cw, const float* cb, const float* w_a, const float* b_a, const float* w_i, const float* b_i,
;                                          const float* lam, int gv, int vloc, int nb, int dir) {
;     ...
; #pragma unroll
;             for (int ct = 0; ct < 8; ++ct) {
;                 f32x4 a = (f32x4){0.f, 0.f, 0.f, 0.f};
; #pragma unroll
;                 for (int ks = 0; ks < 2; ++ks) a = MFMA16(ldfrag(WT + (16 * ct + fr) * LDX + 32 * ks + 8 * fq), xf[ks], a);
;                 Gt[ct] = a;
;             }
; #pragma unroll
;             for (int ct = 0; ct < 4; ++ct) {
;                 const int c0 = 16 * ct + 4 * fq;
;                 const f32x4 ba = *(const LAS f32x4*)(BA + c0), bi = *(const LAS f32x4*)(BI + c0), sp = *(const LAS f32x4*)(SP + c0);
;                 const u32x2 xw = *(const LAS u32x2*)(XCB + t * LDX + c0);
;                 const float xv[4] = {bflo(xw.x), bfhi(xw.x), bflo(xw.y), bfhi(xw.y)};
;                 f32x4 av, uv;
; #pragma unroll
;                 for (int e = 0; e < 4; ++e) {
;                     const float r = sigm(Gt[ct][e] + ba[e]), ig = sigm(Gt[ct + 4][e] + bi[e]);
.LBB0_469:
	s_waitcnt lgkmcnt(0)
	s_barrier
	ds_read_b128 v[64:67], v108
	ds_read_b128 v[92:95], v108 offset:64
	s_mov_b32 s0, 0xf800000
	ds_read_b128 v[228:231], v227 offset:18432
	ds_read_b128 v[232:235], v227 offset:18496
	ds_read_b128 v[236:239], v227 offset:20736
	ds_read_b128 v[240:243], v227 offset:20800
	ds_read_b128 v[244:247], v227 offset:23040
	s_waitcnt lgkmcnt(4)
	v_mfma_f32_16x16x32_bf16 v[84:87], v[228:231], v[64:67], 0
	ds_read_b128 v[228:231], v227 offset:23104
	s_waitcnt lgkmcnt(4)
	v_mfma_f32_16x16x32_bf16 v[84:87], v[232:235], v[92:95], v[84:87]
	ds_read_b128 v[232:235], v227 offset:25344
	s_waitcnt lgkmcnt(4)
	v_mfma_f32_16x16x32_bf16 v[76:79], v[236:239], v[64:67], 0
	ds_read_b128 v[236:239], v227 offset:25408
	s_waitcnt lgkmcnt(4)
	v_mfma_f32_16x16x32_bf16 v[76:79], v[240:243], v[92:95], v[76:79]
	ds_read_b128 v[240:243], v227 offset:27648
	s_waitcnt lgkmcnt(4)
	v_mfma_f32_16x16x32_bf16 v[68:71], v[244:247], v[64:67], 0
	ds_read_b128 v[244:247], v227 offset:27712
	s_waitcnt lgkmcnt(4)
	v_mfma_f32_16x16x32_bf16 v[68:71], v[228:231], v[92:95], v[68:71]
	ds_read_b128 v[228:231], v227 offset:29952
	s_waitcnt lgkmcnt(4)
	v_mfma_f32_16x16x32_bf16 v[60:63], v[232:235], v[64:67], 0
	ds_read_b128 v[232:235], v227 offset:30016
	s_waitcnt lgkmcnt(4)
	v_mfma_f32_16x16x32_bf16 v[60:63], v[236:239], v[92:95], v[60:63]
	ds_read_b128 v[236:239], v227 offset:32256
	s_waitcnt lgkmcnt(4)
	v_mfma_f32_16x16x32_bf16 v[88:91], v[240:243], v[64:67], 0
	ds_read_b128 v[240:243], v227 offset:32320
	s_waitcnt lgkmcnt(4)
	v_mfma_f32_16x16x32_bf16 v[88:91], v[244:247], v[92:95], v[88:91]
	ds_read_b128 v[244:247], v227 offset:34560
	s_waitcnt lgkmcnt(4)
	v_mfma_f32_16x16x32_bf16 v[80:83], v[228:231], v[64:67], 0
	ds_read_b128 v[228:231], v227 offset:34624
	s_waitcnt lgkmcnt(4)
	v_mfma_f32_16x16x32_bf16 v[80:83], v[232:235], v[92:95], v[80:83]
	s_waitcnt lgkmcnt(3)
	v_mfma_f32_16x16x32_bf16 v[72:75], v[236:239], v[64:67], 0
	s_waitcnt lgkmcnt(2)
	v_mfma_f32_16x16x32_bf16 v[72:75], v[240:243], v[92:95], v[72:75]
	s_waitcnt lgkmcnt(1)
	v_mfma_f32_16x16x32_bf16 v[64:67], v[244:247], v[64:67], 0
	s_waitcnt lgkmcnt(0)
	v_mfma_f32_16x16x32_bf16 v[64:67], v[228:231], v[92:95], v[64:67]
	ds_read_b128 v[100:103], v128
	ds_read_b128 v[96:99], v155
	ds_read_b128 v[92:95], v156
	ds_read_b64 v[150:151], v157
	s_waitcnt lgkmcnt(3)
	v_add_f32_e32 v84, v84, v100
	v_mul_f32_e32 v84, 0xbfb8aa3b, v84
	v_exp_f32_e32 v84, v84
	s_waitcnt lgkmcnt(2)
	v_add_f32_e32 v88, v88, v96
	v_add_f32_e32 v85, v85, v101
	v_mul_f32_e32 v85, 0xbfb8aa3b, v85
	v_add_f32_e32 v84, 1.0, v84
	v_rcp_f32_e32 v84, v84
	v_exp_f32_e32 v85, v85
	v_add_f32_e32 v86, v86, v102
	v_mul_f32_e32 v86, 0xbfb8aa3b, v86
	s_waitcnt lgkmcnt(1)
	v_mul_f32_e32 v84, v92, v84
	v_mul_f32_e32 v84, 0xbfb8aa3b, v84
	v_exp_f32_e32 v84, v84
	v_add_f32_e32 v85, 1.0, v85
	v_rcp_f32_e32 v85, v85
	v_exp_f32_e32 v86, v86
	v_sub_f32_e32 v92, 1.0, v84
	v_add_f32_e32 v96, 1.0, v84
	v_mul_f32_e32 v92, v92, v96
	v_max_f32_e32 v92, 0, v92
	v_cmp_gt_f32_e32 vcc, s0, v92
	v_mul_f32_e32 v96, 0x4f800000, v92
	v_mul_f32_e32 v85, v93, v85
	v_cndmask_b32_e32 v92, v92, v96, vcc
	v_sqrt_f32_e32 v96, v92
	v_mul_f32_e32 v85, 0xbfb8aa3b, v85
	v_exp_f32_e32 v85, v85
	v_add_f32_e32 v89, v89, v97
	v_add_u32_e32 v100, -1, v96
	v_fma_f32 v176, -v100, v96, v92
	v_cmp_ge_f32_e64 s[8:9], 0, v176
	v_add_u32_e32 v176, 1, v96
	v_sub_f32_e32 v93, 1.0, v85
	v_cndmask_b32_e64 v100, v96, v100, s[8:9]
	v_fma_f32 v96, -v176, v96, v92
	v_cmp_lt_f32_e64 s[8:9], 0, v96
	v_add_f32_e32 v86, 1.0, v86
	v_mul_f32_e32 v88, 0xbfb8aa3b, v88
	v_cndmask_b32_e64 v96, v100, v176, s[8:9]
	v_mul_f32_e32 v100, 0x37800000, v96
	v_cndmask_b32_e32 v96, v96, v100, vcc
	v_cmp_class_f32_e32 vcc, v92, v174
	v_mul_f32_e32 v89, 0xbfb8aa3b, v89
	v_rcp_f32_e32 v86, v86
	v_cndmask_b32_e32 v92, v96, v92, vcc
	v_add_f32_e32 v96, 1.0, v85
	v_mul_f32_e32 v93, v93, v96
	v_max_f32_e32 v93, 0, v93
	v_cmp_gt_f32_e32 vcc, s0, v93
	v_mul_f32_e32 v96, 0x4f800000, v93
	v_exp_f32_e32 v88, v88
	v_cndmask_b32_e32 v93, v93, v96, vcc
	v_sqrt_f32_e32 v96, v93
	v_exp_f32_e32 v89, v89
	v_mul_f32_e32 v86, v94, v86
	v_add_f32_e32 v88, 1.0, v88
	v_add_u32_e32 v97, -1, v96
	v_fma_f32 v100, -v97, v96, v93
	v_cmp_ge_f32_e64 s[8:9], 0, v100
	v_add_u32_e32 v100, 1, v96
	v_add_f32_e32 v89, 1.0, v89
	v_cndmask_b32_e64 v97, v96, v97, s[8:9]
	v_fma_f32 v96, -v100, v96, v93
	v_cmp_lt_f32_e64 s[8:9], 0, v96
	v_mul_f32_e32 v86, 0xbfb8aa3b, v86
	v_rcp_f32_e32 v88, v88
	v_rcp_f32_e32 v89, v89
	v_cndmask_b32_e64 v96, v97, v100, s[8:9]
	v_exp_f32_e32 v86, v86
	v_mul_f32_e32 v97, 0x37800000, v96
	v_cndmask_b32_e32 v96, v96, v97, vcc
	v_cmp_class_f32_e32 vcc, v93, v174
	v_add_f32_e32 v87, v87, v103
	v_mul_f32_e32 v87, 0xbfb8aa3b, v87
	v_cndmask_b32_e32 v93, v96, v93, vcc
	v_pk_mul_f32 v[88:89], v[88:89], v[92:93]
	v_sub_f32_e32 v92, 1.0, v86
	v_add_f32_e32 v93, 1.0, v86
	v_mul_f32_e32 v92, v92, v93
	v_max_f32_e32 v92, 0, v92
	v_exp_f32_e32 v87, v87
	v_cmp_gt_f32_e32 vcc, s0, v92
	v_mul_f32_e32 v93, 0x4f800000, v92
	s_waitcnt lgkmcnt(0)
; #define LAS __attribute__((address_space(3)))
; __device__ __forceinline__ float sigm(float x) { return __builtin_amdgcn_rcpf(1.0f + __expf(-x)); }
; __device__ __forceinline__ void lru_item(LAS unsigned char* lds, const bf16* proj, bf16* yout, const float* cw, const float* cb, const float* w_a, const float* b_a, const float* w_i, const float* b_i,
;                                          const float* lam, int gv, int vloc, int nb, int dir) {
;     ...
; #pragma unroll
;             for (int ct = 0; ct < 4; ++ct) {
;                 const int c0 = 16 * ct + 4 * fq;
;                 const f32x4 ba = *(const LAS f32x4*)(BA + c0), bi = *(const LAS f32x4*)(BI + c0), sp = *(const LAS f32x4*)(SP + c0);
;                 const u32x2 xw = *(const LAS u32x2*)(XCB + t * LDX + c0);
;                 const float xv[4] = {bflo(xw.x), bfhi(xw.x), bflo(xw.y), bfhi(xw.y)};
;                 f32x4 av, uv;
; #pragma unroll
;                 for (int e = 0; e < 4; ++e) {
;                     const float r = sigm(Gt[ct][e] + ba[e]), ig = sigm(Gt[ct + 4][e] + bi[e]);
;                     const float la = -r * sp[e];
;                     const float a = __expf(la);
;                     av[e] = a;
;                     uv[e] = sqrtf(fmaxf((1.0f - a) * (1.0f + a), 0.f)) * ig * xv[e];
;                 }
;                 *(LAS f32x4*)(AA + t * 64 + c0) = av; *(LAS f32x4*)(UU + t * 64 + c0) = uv;
;             }
	v_lshlrev_b32_e32 v96, 16, v150
	v_cndmask_b32_e32 v92, v92, v93, vcc
	v_sqrt_f32_e32 v93, v92
	v_add_f32_e32 v87, 1.0, v87
	v_rcp_f32_e32 v87, v87
	v_and_b32_e32 v97, 0xffff0000, v150
	v_add_u32_e32 v94, -1, v93
	v_pk_mul_f32 v[88:89], v[88:89], v[96:97]
	v_fma_f32 v96, -v94, v93, v92
	v_cmp_ge_f32_e64 s[8:9], 0, v96
	v_add_u32_e32 v96, 1, v93
	v_mul_f32_e32 v87, v95, v87
	v_cndmask_b32_e64 v94, v93, v94, s[8:9]
	v_fma_f32 v93, -v96, v93, v92
	v_mul_f32_e32 v87, 0xbfb8aa3b, v87
	v_cmp_lt_f32_e64 s[8:9], 0, v93
	v_exp_f32_e32 v87, v87
	v_add_f32_e32 v90, v90, v98
	v_cndmask_b32_e64 v93, v94, v96, s[8:9]
	v_mul_f32_e32 v94, 0x37800000, v93
	v_cndmask_b32_e32 v93, v93, v94, vcc
	v_cmp_class_f32_e32 vcc, v92, v174
	v_add_f32_e32 v94, 1.0, v87
	v_add_f32_e32 v91, v91, v99
	v_cndmask_b32_e32 v92, v93, v92, vcc
	v_sub_f32_e32 v93, 1.0, v87
	v_mul_f32_e32 v93, v93, v94
	v_max_f32_e32 v93, 0, v93
	v_cmp_gt_f32_e32 vcc, s0, v93
	v_mul_f32_e32 v94, 0x4f800000, v93
	v_mul_f32_e32 v90, 0xbfb8aa3b, v90
	v_cndmask_b32_e32 v93, v93, v94, vcc
	v_sqrt_f32_e32 v94, v93
	v_mul_f32_e32 v91, 0xbfb8aa3b, v91
	v_exp_f32_e32 v90, v90
	v_exp_f32_e32 v91, v91
	v_add_u32_e32 v95, -1, v94
	v_fma_f32 v96, -v95, v94, v93
	v_cmp_ge_f32_e64 s[8:9], 0, v96
	v_add_u32_e32 v96, 1, v94
	v_add_f32_e32 v90, 1.0, v90
	v_cndmask_b32_e64 v95, v94, v95, s[8:9]
	v_fma_f32 v94, -v96, v94, v93
	v_add_f32_e32 v91, 1.0, v91
	v_cmp_lt_f32_e64 s[8:9], 0, v94
	v_rcp_f32_e32 v90, v90
	v_rcp_f32_e32 v91, v91
	v_cndmask_b32_e64 v94, v95, v96, s[8:9]
	v_mul_f32_e32 v95, 0x37800000, v94
	v_cndmask_b32_e32 v94, v94, v95, vcc
	v_cmp_class_f32_e32 vcc, v93, v174
	v_and_b32_e32 v95, 0xffff0000, v151
	s_nop 0
	v_cndmask_b32_e32 v93, v94, v93, vcc
	v_lshlrev_b32_e32 v94, 16, v151
	v_pk_mul_f32 v[90:91], v[90:91], v[92:93]
	s_nop 0
	v_pk_mul_f32 v[90:91], v[90:91], v[94:95]
	ds_write_b128 v112, v[84:87] offset:36864
	ds_write_b128 v113, v[88:91]
	ds_read_b128 v[92:95], v158
	ds_read_b128 v[88:91], v159
	ds_read_b128 v[84:87], v160
	ds_read_b64 v[96:97], v157 offset:32
	s_waitcnt lgkmcnt(3)
	v_add_f32_e32 v76, v76, v92
	v_mul_f32_e32 v76, 0xbfb8aa3b, v76
	v_exp_f32_e32 v76, v76
	s_waitcnt lgkmcnt(2)
	v_add_f32_e32 v80, v80, v88
	v_add_f32_e32 v77, v77, v93
	v_mul_f32_e32 v77, 0xbfb8aa3b, v77
	v_add_f32_e32 v76, 1.0, v76
	v_rcp_f32_e32 v76, v76
	v_exp_f32_e32 v77, v77
	v_add_f32_e32 v78, v78, v94
	v_mul_f32_e32 v78, 0xbfb8aa3b, v78
	s_waitcnt lgkmcnt(1)
	v_mul_f32_e32 v76, v84, v76
	v_mul_f32_e32 v76, 0xbfb8aa3b, v76
	v_exp_f32_e32 v76, v76
	v_add_f32_e32 v77, 1.0, v77
	v_rcp_f32_e32 v77, v77
	v_exp_f32_e32 v78, v78
	v_sub_f32_e32 v84, 1.0, v76
	v_add_f32_e32 v88, 1.0, v76
	v_mul_f32_e32 v84, v84, v88
	v_max_f32_e32 v84, 0, v84
	v_cmp_gt_f32_e32 vcc, s0, v84
	v_mul_f32_e32 v88, 0x4f800000, v84
	v_mul_f32_e32 v77, v85, v77
	v_cndmask_b32_e32 v84, v84, v88, vcc
	v_sqrt_f32_e32 v88, v84
	v_mul_f32_e32 v77, 0xbfb8aa3b, v77
	v_exp_f32_e32 v77, v77
	v_add_f32_e32 v81, v81, v89
	v_add_u32_e32 v92, -1, v88
	v_fma_f32 v98, -v92, v88, v84
	v_cmp_ge_f32_e64 s[8:9], 0, v98
	v_add_u32_e32 v98, 1, v88
	v_sub_f32_e32 v85, 1.0, v77
	v_cndmask_b32_e64 v92, v88, v92, s[8:9]
	v_fma_f32 v88, -v98, v88, v84
	v_cmp_lt_f32_e64 s[8:9], 0, v88
	v_add_f32_e32 v78, 1.0, v78
	v_mul_f32_e32 v80, 0xbfb8aa3b, v80
	v_cndmask_b32_e64 v88, v92, v98, s[8:9]
	v_mul_f32_e32 v92, 0x37800000, v88
	v_cndmask_b32_e32 v88, v88, v92, vcc
	v_cmp_class_f32_e32 vcc, v84, v174
	v_mul_f32_e32 v81, 0xbfb8aa3b, v81
	v_rcp_f32_e32 v78, v78
	v_cndmask_b32_e32 v84, v88, v84, vcc
	v_add_f32_e32 v88, 1.0, v77
	v_mul_f32_e32 v85, v85, v88
	v_max_f32_e32 v85, 0, v85
	v_cmp_gt_f32_e32 vcc, s0, v85
	v_mul_f32_e32 v88, 0x4f800000, v85
	v_exp_f32_e32 v80, v80
	v_cndmask_b32_e32 v85, v85, v88, vcc
	v_sqrt_f32_e32 v88, v85
	v_exp_f32_e32 v81, v81
	v_mul_f32_e32 v78, v86, v78
	v_add_f32_e32 v80, 1.0, v80
	v_add_u32_e32 v89, -1, v88
	v_fma_f32 v92, -v89, v88, v85
	v_cmp_ge_f32_e64 s[8:9], 0, v92
	v_add_u32_e32 v92, 1, v88
	v_add_f32_e32 v81, 1.0, v81
	v_cndmask_b32_e64 v89, v88, v89, s[8:9]
	v_fma_f32 v88, -v92, v88, v85
	v_cmp_lt_f32_e64 s[8:9], 0, v88
	v_mul_f32_e32 v78, 0xbfb8aa3b, v78
	v_rcp_f32_e32 v80, v80
	v_rcp_f32_e32 v81, v81
	v_cndmask_b32_e64 v88, v89, v92, s[8:9]
	v_exp_f32_e32 v78, v78
	v_mul_f32_e32 v89, 0x37800000, v88
	v_cndmask_b32_e32 v88, v88, v89, vcc
	v_cmp_class_f32_e32 vcc, v85, v174
	v_add_f32_e32 v79, v79, v95
	v_mul_f32_e32 v79, 0xbfb8aa3b, v79
	v_cndmask_b32_e32 v85, v88, v85, vcc
	v_pk_mul_f32 v[80:81], v[80:81], v[84:85]
	v_sub_f32_e32 v84, 1.0, v78
	v_add_f32_e32 v85, 1.0, v78
	v_mul_f32_e32 v84, v84, v85
	v_max_f32_e32 v84, 0, v84
	v_exp_f32_e32 v79, v79
	v_cmp_gt_f32_e32 vcc, s0, v84
	v_mul_f32_e32 v85, 0x4f800000, v84
	s_waitcnt lgkmcnt(0)
; #define LAS __attribute__((address_space(3)))
; __device__ __forceinline__ float sigm(float x) { return __builtin_amdgcn_rcpf(1.0f + __expf(-x)); }
; __device__ __forceinline__ void lru_item(LAS unsigned char* lds, const bf16* proj, bf16* yout, const float* cw, const float* cb, const float* w_a, const float* b_a, const float* w_i, const float* b_i,
;                                          const float* lam, int gv, int vloc, int nb, int dir) {
;     ...
; #pragma unroll
;             for (int ct = 0; ct < 4; ++ct) {
;                 const int c0 = 16 * ct + 4 * fq;
;                 const f32x4 ba = *(const LAS f32x4*)(BA + c0), bi = *(const LAS f32x4*)(BI + c0), sp = *(const LAS f32x4*)(SP + c0);
;                 const u32x2 xw = *(const LAS u32x2*)(XCB + t * LDX + c0);
;                 const float xv[4] = {bflo(xw.x), bfhi(xw.x), bflo(xw.y), bfhi(xw.y)};
;                 f32x4 av, uv;
; #pragma unroll
;                 for (int e = 0; e < 4; ++e) {
;                     const float r = sigm(Gt[ct][e] + ba[e]), ig = sigm(Gt[ct + 4][e] + bi[e]);
;                     const float la = -r * sp[e];
;                     const float a = __expf(la);
;                     av[e] = a;
;                     uv[e] = sqrtf(fmaxf((1.0f - a) * (1.0f + a), 0.f)) * ig * xv[e];
;                 }
;                 *(LAS f32x4*)(AA + t * 64 + c0) = av; *(LAS f32x4*)(UU + t * 64 + c0) = uv;
;             }
	v_lshlrev_b32_e32 v88, 16, v96
	v_cndmask_b32_e32 v84, v84, v85, vcc
	v_sqrt_f32_e32 v85, v84
	v_add_f32_e32 v79, 1.0, v79
	v_rcp_f32_e32 v79, v79
	v_and_b32_e32 v89, 0xffff0000, v96
	v_add_u32_e32 v86, -1, v85
	v_pk_mul_f32 v[80:81], v[80:81], v[88:89]
	v_fma_f32 v88, -v86, v85, v84
	v_cmp_ge_f32_e64 s[8:9], 0, v88
	v_add_u32_e32 v88, 1, v85
	v_mul_f32_e32 v79, v87, v79
	v_cndmask_b32_e64 v86, v85, v86, s[8:9]
	v_fma_f32 v85, -v88, v85, v84
	v_mul_f32_e32 v79, 0xbfb8aa3b, v79
	v_cmp_lt_f32_e64 s[8:9], 0, v85
	v_exp_f32_e32 v79, v79
	v_add_f32_e32 v82, v82, v90
	v_cndmask_b32_e64 v85, v86, v88, s[8:9]
	v_mul_f32_e32 v86, 0x37800000, v85
	v_cndmask_b32_e32 v85, v85, v86, vcc
	v_cmp_class_f32_e32 vcc, v84, v174
	v_add_f32_e32 v86, 1.0, v79
	v_add_f32_e32 v83, v83, v91
	v_cndmask_b32_e32 v84, v85, v84, vcc
	v_sub_f32_e32 v85, 1.0, v79
	v_mul_f32_e32 v85, v85, v86
	v_max_f32_e32 v85, 0, v85
	v_cmp_gt_f32_e32 vcc, s0, v85
	v_mul_f32_e32 v86, 0x4f800000, v85
	v_mul_f32_e32 v82, 0xbfb8aa3b, v82
	v_cndmask_b32_e32 v85, v85, v86, vcc
	v_sqrt_f32_e32 v86, v85
	v_mul_f32_e32 v83, 0xbfb8aa3b, v83
	v_exp_f32_e32 v82, v82
	v_exp_f32_e32 v83, v83
	v_add_u32_e32 v87, -1, v86
	v_fma_f32 v88, -v87, v86, v85
	v_cmp_ge_f32_e64 s[8:9], 0, v88
	v_add_u32_e32 v88, 1, v86
	v_add_f32_e32 v82, 1.0, v82
	v_cndmask_b32_e64 v87, v86, v87, s[8:9]
	v_fma_f32 v86, -v88, v86, v85
	v_add_f32_e32 v83, 1.0, v83
	v_cmp_lt_f32_e64 s[8:9], 0, v86
	v_rcp_f32_e32 v82, v82
	v_rcp_f32_e32 v83, v83
	v_cndmask_b32_e64 v86, v87, v88, s[8:9]
	v_mul_f32_e32 v87, 0x37800000, v86
	v_cndmask_b32_e32 v86, v86, v87, vcc
	v_cmp_class_f32_e32 vcc, v85, v174
	v_and_b32_e32 v87, 0xffff0000, v97
	s_nop 0
	v_cndmask_b32_e32 v85, v86, v85, vcc
	v_lshlrev_b32_e32 v86, 16, v97
	v_pk_mul_f32 v[82:83], v[82:83], v[84:85]
	s_nop 0
	v_pk_mul_f32 v[82:83], v[82:83], v[86:87]
	ds_write_b128 v112, v[76:79] offset:36928
	ds_write_b128 v113, v[80:83] offset:64
	ds_read_b128 v[84:87], v161
	ds_read_b128 v[80:83], v162
	ds_read_b128 v[76:79], v163
	ds_read_b64 v[88:89], v157 offset:64
	s_waitcnt lgkmcnt(3)
	v_add_f32_e32 v68, v68, v84
	v_mul_f32_e32 v68, 0xbfb8aa3b, v68
	v_exp_f32_e32 v68, v68
	s_waitcnt lgkmcnt(2)
	v_add_f32_e32 v72, v72, v80
	v_add_f32_e32 v69, v69, v85
	v_mul_f32_e32 v69, 0xbfb8aa3b, v69
	v_add_f32_e32 v68, 1.0, v68
	v_rcp_f32_e32 v68, v68
	v_exp_f32_e32 v69, v69
	v_add_f32_e32 v70, v70, v86
	v_mul_f32_e32 v70, 0xbfb8aa3b, v70
	s_waitcnt lgkmcnt(1)
	v_mul_f32_e32 v68, v76, v68
	v_mul_f32_e32 v68, 0xbfb8aa3b, v68
	v_exp_f32_e32 v68, v68
	v_add_f32_e32 v69, 1.0, v69
	v_rcp_f32_e32 v69, v69
	v_exp_f32_e32 v70, v70
	v_sub_f32_e32 v76, 1.0, v68
	v_add_f32_e32 v80, 1.0, v68
	v_mul_f32_e32 v76, v76, v80
	v_max_f32_e32 v76, 0, v76
	v_cmp_gt_f32_e32 vcc, s0, v76
	v_mul_f32_e32 v80, 0x4f800000, v76
	v_mul_f32_e32 v69, v77, v69
	v_cndmask_b32_e32 v76, v76, v80, vcc
	v_sqrt_f32_e32 v80, v76
	v_mul_f32_e32 v69, 0xbfb8aa3b, v69
	v_exp_f32_e32 v69, v69
	v_add_f32_e32 v73, v73, v81
	v_add_u32_e32 v84, -1, v80
	v_fma_f32 v90, -v84, v80, v76
	v_cmp_ge_f32_e64 s[8:9], 0, v90
	v_add_u32_e32 v90, 1, v80
	v_sub_f32_e32 v77, 1.0, v69
	v_cndmask_b32_e64 v84, v80, v84, s[8:9]
	v_fma_f32 v80, -v90, v80, v76
	v_cmp_lt_f32_e64 s[8:9], 0, v80
	v_add_f32_e32 v70, 1.0, v70
	v_mul_f32_e32 v72, 0xbfb8aa3b, v72
	v_cndmask_b32_e64 v80, v84, v90, s[8:9]
	v_mul_f32_e32 v84, 0x37800000, v80
	v_cndmask_b32_e32 v80, v80, v84, vcc
	v_cmp_class_f32_e32 vcc, v76, v174
	v_mul_f32_e32 v73, 0xbfb8aa3b, v73
	v_rcp_f32_e32 v70, v70
	v_cndmask_b32_e32 v76, v80, v76, vcc
	v_add_f32_e32 v80, 1.0, v69
	v_mul_f32_e32 v77, v77, v80
	v_max_f32_e32 v77, 0, v77
	v_cmp_gt_f32_e32 vcc, s0, v77
	v_mul_f32_e32 v80, 0x4f800000, v77
	v_exp_f32_e32 v72, v72
	v_cndmask_b32_e32 v77, v77, v80, vcc
	v_sqrt_f32_e32 v80, v77
	v_exp_f32_e32 v73, v73
	v_mul_f32_e32 v70, v78, v70
	v_add_f32_e32 v72, 1.0, v72
	v_add_u32_e32 v81, -1, v80
	v_fma_f32 v84, -v81, v80, v77
	v_cmp_ge_f32_e64 s[8:9], 0, v84
	v_add_u32_e32 v84, 1, v80
	v_add_f32_e32 v73, 1.0, v73
	v_cndmask_b32_e64 v81, v80, v81, s[8:9]
	v_fma_f32 v80, -v84, v80, v77
	v_cmp_lt_f32_e64 s[8:9], 0, v80
	v_mul_f32_e32 v70, 0xbfb8aa3b, v70
	v_rcp_f32_e32 v72, v72
	v_rcp_f32_e32 v73, v73
	v_cndmask_b32_e64 v80, v81, v84, s[8:9]
	v_exp_f32_e32 v70, v70
	v_mul_f32_e32 v81, 0x37800000, v80
	v_cndmask_b32_e32 v80, v80, v81, vcc
	v_cmp_class_f32_e32 vcc, v77, v174
	v_add_f32_e32 v71, v71, v87
	v_mul_f32_e32 v71, 0xbfb8aa3b, v71
	v_cndmask_b32_e32 v77, v80, v77, vcc
	v_pk_mul_f32 v[72:73], v[72:73], v[76:77]
	v_sub_f32_e32 v76, 1.0, v70
	v_add_f32_e32 v77, 1.0, v70
	v_mul_f32_e32 v76, v76, v77
	v_max_f32_e32 v76, 0, v76
	v_exp_f32_e32 v71, v71
	v_cmp_gt_f32_e32 vcc, s0, v76
	v_mul_f32_e32 v77, 0x4f800000, v76
	s_waitcnt lgkmcnt(0)
; #define LAS __attribute__((address_space(3)))
; __device__ __forceinline__ float sigm(float x) { return __builtin_amdgcn_rcpf(1.0f + __expf(-x)); }
; __device__ __forceinline__ void lru_item(LAS unsigned char* lds, const bf16* proj, bf16* yout, const float* cw, const float* cb, const float* w_a, const float* b_a, const float* w_i, const float* b_i,
;                                          const float* lam, int gv, int vloc, int nb, int dir) {
;     ...
; #pragma unroll
;             for (int ct = 0; ct < 4; ++ct) {
;                 const int c0 = 16 * ct + 4 * fq;
;                 const f32x4 ba = *(const LAS f32x4*)(BA + c0), bi = *(const LAS f32x4*)(BI + c0), sp = *(const LAS f32x4*)(SP + c0);
;                 const u32x2 xw = *(const LAS u32x2*)(XCB + t * LDX + c0);
;                 const float xv[4] = {bflo(xw.x), bfhi(xw.x), bflo(xw.y), bfhi(xw.y)};
;                 f32x4 av, uv;
; #pragma unroll
;                 for (int e = 0; e < 4; ++e) {
;                     const float r = sigm(Gt[ct][e] + ba[e]), ig = sigm(Gt[ct + 4][e] + bi[e]);
;                     const float la = -r * sp[e];
;                     const float a = __expf(la);
;                     av[e] = a;
;                     uv[e] = sqrtf(fmaxf((1.0f - a) * (1.0f + a), 0.f)) * ig * xv[e];
;                 }
;                 *(LAS f32x4*)(AA + t * 64 + c0) = av; *(LAS f32x4*)(UU + t * 64 + c0) = uv;
;             }
;         }
;         __syncthreads();
	v_lshlrev_b32_e32 v80, 16, v88
	v_cndmask_b32_e32 v76, v76, v77, vcc
	v_sqrt_f32_e32 v77, v76
	v_add_f32_e32 v71, 1.0, v71
	v_rcp_f32_e32 v71, v71
	v_and_b32_e32 v81, 0xffff0000, v88
	v_add_u32_e32 v78, -1, v77
	v_pk_mul_f32 v[72:73], v[72:73], v[80:81]
	v_fma_f32 v80, -v78, v77, v76
	v_cmp_ge_f32_e64 s[8:9], 0, v80
	v_add_u32_e32 v80, 1, v77
	v_mul_f32_e32 v71, v79, v71
	v_cndmask_b32_e64 v78, v77, v78, s[8:9]
	v_fma_f32 v77, -v80, v77, v76
	v_mul_f32_e32 v71, 0xbfb8aa3b, v71
	v_cmp_lt_f32_e64 s[8:9], 0, v77
	v_exp_f32_e32 v71, v71
	v_add_f32_e32 v74, v74, v82
	v_cndmask_b32_e64 v77, v78, v80, s[8:9]
	v_mul_f32_e32 v78, 0x37800000, v77
	v_cndmask_b32_e32 v77, v77, v78, vcc
	v_cmp_class_f32_e32 vcc, v76, v174
	v_add_f32_e32 v78, 1.0, v71
	v_add_f32_e32 v75, v75, v83
	v_cndmask_b32_e32 v76, v77, v76, vcc
	v_sub_f32_e32 v77, 1.0, v71
	v_mul_f32_e32 v77, v77, v78
	v_max_f32_e32 v77, 0, v77
	v_cmp_gt_f32_e32 vcc, s0, v77
	v_mul_f32_e32 v78, 0x4f800000, v77
	v_mul_f32_e32 v74, 0xbfb8aa3b, v74
	v_cndmask_b32_e32 v77, v77, v78, vcc
	v_sqrt_f32_e32 v78, v77
	v_mul_f32_e32 v75, 0xbfb8aa3b, v75
	v_exp_f32_e32 v74, v74
	v_exp_f32_e32 v75, v75
	v_add_u32_e32 v79, -1, v78
	v_fma_f32 v80, -v79, v78, v77
	v_cmp_ge_f32_e64 s[8:9], 0, v80
	v_add_u32_e32 v80, 1, v78
	v_add_f32_e32 v74, 1.0, v74
	v_cndmask_b32_e64 v79, v78, v79, s[8:9]
	v_fma_f32 v78, -v80, v78, v77
	v_add_f32_e32 v75, 1.0, v75
	v_cmp_lt_f32_e64 s[8:9], 0, v78
	v_rcp_f32_e32 v74, v74
	v_rcp_f32_e32 v75, v75
	v_cndmask_b32_e64 v78, v79, v80, s[8:9]
	v_mul_f32_e32 v79, 0x37800000, v78
	v_cndmask_b32_e32 v78, v78, v79, vcc
	v_cmp_class_f32_e32 vcc, v77, v174
	v_and_b32_e32 v79, 0xffff0000, v89
	s_nop 0
	v_cndmask_b32_e32 v77, v78, v77, vcc
	v_lshlrev_b32_e32 v78, 16, v89
	v_pk_mul_f32 v[74:75], v[74:75], v[76:77]
	s_nop 0
	v_pk_mul_f32 v[74:75], v[74:75], v[78:79]
	ds_write_b128 v112, v[68:71] offset:36992
	ds_write_b128 v113, v[72:75] offset:128
	ds_read_b128 v[76:79], v164
	ds_read_b128 v[72:75], v165
	ds_read_b128 v[68:71], v166
	ds_read_b64 v[80:81], v157 offset:96
	s_waitcnt lgkmcnt(3)
	v_add_f32_e32 v60, v60, v76
	v_mul_f32_e32 v60, 0xbfb8aa3b, v60
	v_exp_f32_e32 v60, v60
	s_waitcnt lgkmcnt(2)
	v_add_f32_e32 v64, v64, v72
	v_add_f32_e32 v61, v61, v77
	v_mul_f32_e32 v61, 0xbfb8aa3b, v61
	v_add_f32_e32 v60, 1.0, v60
	v_rcp_f32_e32 v60, v60
	v_exp_f32_e32 v61, v61
	v_add_f32_e32 v62, v62, v78
	v_mul_f32_e32 v62, 0xbfb8aa3b, v62
	s_waitcnt lgkmcnt(1)
	v_mul_f32_e32 v60, v68, v60
	v_mul_f32_e32 v60, 0xbfb8aa3b, v60
	v_exp_f32_e32 v60, v60
	v_add_f32_e32 v61, 1.0, v61
	v_rcp_f32_e32 v61, v61
	v_exp_f32_e32 v62, v62
	v_sub_f32_e32 v68, 1.0, v60
	v_add_f32_e32 v72, 1.0, v60
	v_mul_f32_e32 v68, v68, v72
	v_max_f32_e32 v68, 0, v68
	v_cmp_gt_f32_e32 vcc, s0, v68
	v_mul_f32_e32 v72, 0x4f800000, v68
	v_mul_f32_e32 v61, v69, v61
	v_cndmask_b32_e32 v68, v68, v72, vcc
	v_sqrt_f32_e32 v72, v68
	v_mul_f32_e32 v61, 0xbfb8aa3b, v61
	v_exp_f32_e32 v61, v61
	v_add_f32_e32 v65, v65, v73
	v_add_u32_e32 v76, -1, v72
	v_fma_f32 v82, -v76, v72, v68
	v_cmp_ge_f32_e64 s[8:9], 0, v82
	v_add_u32_e32 v82, 1, v72
	v_sub_f32_e32 v69, 1.0, v61
	v_cndmask_b32_e64 v76, v72, v76, s[8:9]
	v_fma_f32 v72, -v82, v72, v68
	v_cmp_lt_f32_e64 s[8:9], 0, v72
	v_add_f32_e32 v62, 1.0, v62
	v_mul_f32_e32 v64, 0xbfb8aa3b, v64
	v_cndmask_b32_e64 v72, v76, v82, s[8:9]
	v_mul_f32_e32 v76, 0x37800000, v72
	v_cndmask_b32_e32 v72, v72, v76, vcc
	v_cmp_class_f32_e32 vcc, v68, v174
	v_mul_f32_e32 v65, 0xbfb8aa3b, v65
	v_rcp_f32_e32 v62, v62
	v_cndmask_b32_e32 v68, v72, v68, vcc
	v_add_f32_e32 v72, 1.0, v61
	v_mul_f32_e32 v69, v69, v72
	v_max_f32_e32 v69, 0, v69
	v_cmp_gt_f32_e32 vcc, s0, v69
	v_mul_f32_e32 v72, 0x4f800000, v69
	v_exp_f32_e32 v64, v64
	v_cndmask_b32_e32 v69, v69, v72, vcc
	v_sqrt_f32_e32 v72, v69
	v_exp_f32_e32 v65, v65
	v_mul_f32_e32 v62, v70, v62
	v_add_f32_e32 v64, 1.0, v64
	v_add_u32_e32 v73, -1, v72
	v_fma_f32 v76, -v73, v72, v69
	v_cmp_ge_f32_e64 s[8:9], 0, v76
	v_add_u32_e32 v76, 1, v72
	v_add_f32_e32 v65, 1.0, v65
	v_cndmask_b32_e64 v73, v72, v73, s[8:9]
	v_fma_f32 v72, -v76, v72, v69
	v_cmp_lt_f32_e64 s[8:9], 0, v72
	v_mul_f32_e32 v62, 0xbfb8aa3b, v62
	v_rcp_f32_e32 v64, v64
	v_rcp_f32_e32 v65, v65
	v_cndmask_b32_e64 v72, v73, v76, s[8:9]
	v_exp_f32_e32 v62, v62
	v_mul_f32_e32 v73, 0x37800000, v72
	v_cndmask_b32_e32 v72, v72, v73, vcc
	v_cmp_class_f32_e32 vcc, v69, v174
	v_add_f32_e32 v63, v63, v79
	v_mul_f32_e32 v63, 0xbfb8aa3b, v63
	v_cndmask_b32_e32 v69, v72, v69, vcc
	v_pk_mul_f32 v[64:65], v[64:65], v[68:69]
	v_sub_f32_e32 v68, 1.0, v62
	v_add_f32_e32 v69, 1.0, v62
	v_mul_f32_e32 v68, v68, v69
	v_max_f32_e32 v68, 0, v68
	v_exp_f32_e32 v63, v63
	v_cmp_gt_f32_e32 vcc, s0, v68
	v_mul_f32_e32 v69, 0x4f800000, v68
	s_waitcnt lgkmcnt(0)
	v_lshlrev_b32_e32 v72, 16, v80
	v_cndmask_b32_e32 v68, v68, v69, vcc
	v_sqrt_f32_e32 v69, v68
	v_add_f32_e32 v63, 1.0, v63
	v_rcp_f32_e32 v63, v63
	v_and_b32_e32 v73, 0xffff0000, v80
	v_add_u32_e32 v70, -1, v69
	v_pk_mul_f32 v[64:65], v[64:65], v[72:73]
	v_fma_f32 v72, -v70, v69, v68
	v_cmp_ge_f32_e64 s[8:9], 0, v72
	v_add_u32_e32 v72, 1, v69
	v_mul_f32_e32 v63, v71, v63
	v_cndmask_b32_e64 v70, v69, v70, s[8:9]
	v_fma_f32 v69, -v72, v69, v68
	v_mul_f32_e32 v63, 0xbfb8aa3b, v63
	v_cmp_lt_f32_e64 s[8:9], 0, v69
	v_exp_f32_e32 v63, v63
	v_add_f32_e32 v66, v66, v74
	v_cndmask_b32_e64 v69, v70, v72, s[8:9]
	v_mul_f32_e32 v70, 0x37800000, v69
	v_cndmask_b32_e32 v69, v69, v70, vcc
	v_cmp_class_f32_e32 vcc, v68, v174
	v_add_f32_e32 v70, 1.0, v63
	v_add_f32_e32 v67, v67, v75
	v_cndmask_b32_e32 v68, v69, v68, vcc
	v_sub_f32_e32 v69, 1.0, v63
	v_mul_f32_e32 v69, v69, v70
	v_max_f32_e32 v69, 0, v69
	v_cmp_gt_f32_e32 vcc, s0, v69
	v_mul_f32_e32 v70, 0x4f800000, v69
	v_mul_f32_e32 v66, 0xbfb8aa3b, v66
	v_cndmask_b32_e32 v69, v69, v70, vcc
	v_sqrt_f32_e32 v70, v69
	v_mul_f32_e32 v67, 0xbfb8aa3b, v67
	v_exp_f32_e32 v66, v66
	v_exp_f32_e32 v67, v67
	v_add_u32_e32 v71, -1, v70
	v_fma_f32 v72, -v71, v70, v69
	v_cmp_ge_f32_e64 s[8:9], 0, v72
	v_add_u32_e32 v72, 1, v70
	v_add_f32_e32 v66, 1.0, v66
	v_cndmask_b32_e64 v71, v70, v71, s[8:9]
	v_fma_f32 v70, -v72, v70, v69
	v_add_f32_e32 v67, 1.0, v67
	v_cmp_lt_f32_e64 s[8:9], 0, v70
	v_rcp_f32_e32 v66, v66
	v_rcp_f32_e32 v67, v67
	v_cndmask_b32_e64 v70, v71, v72, s[8:9]
	v_mul_f32_e32 v71, 0x37800000, v70
	v_cndmask_b32_e32 v70, v70, v71, vcc
	v_cmp_class_f32_e32 vcc, v69, v174
	v_and_b32_e32 v71, 0xffff0000, v81
	s_lshl_b32 s0, s15, 6
	v_cndmask_b32_e32 v69, v70, v69, vcc
	v_lshlrev_b32_e32 v70, 16, v81
	v_pk_mul_f32 v[66:67], v[66:67], v[68:69]
	s_and_b32 s24, s0, 64
	v_pk_mul_f32 v[66:67], v[66:67], v[70:71]
	ds_write_b128 v112, v[60:63] offset:37056
	ds_write_b128 v113, v[64:67] offset:192
	s_waitcnt lgkmcnt(0)
	s_barrier
; __device__ __forceinline__ void lru_item(LAS unsigned char* lds, const bf16* proj, bf16* yout, const float* cw, const float* cb, const float* w_a, const float* b_a, const float* w_i, const float* b_i,
;                                          const float* lam, int gv, int vloc, int nb, int dir) {
;     ...
;         {
;             const int ch = tid & 63, seg = tid >> 6;
;             float Pp = 1.f, h = 0.f;
; #pragma unroll
;             for (int k = 0; k < 16; ++k) { const int o = seg * 16 + k, tt = dir ? 127 - o : o; const float a = AA[tt * 64 + ch], u = UU[tt * 64 + ch]; h = a * h + u; Pp *= a; }
;             AGG[(seg * 64 + ch) * 2] = Pp; AGG[(seg * 64 + ch) * 2 + 1] = h;
;             __syncthreads();
;             float cin = CARRY[(c & 1) * 64 + ch];
;             for (int s = 0; s < seg; ++s) cin = AGG[(s * 64 + ch) * 2] * cin + AGG[(s * 64 + ch) * 2 + 1];
	ds_read_b32 v60, v167 offset:36864
	ds_read_b32 v61, v168
	ds_read_b32 v62, v169 offset:36864
	ds_read_b32 v63, v195
	s_waitcnt lgkmcnt(2)
	v_fmac_f32_e32 v61, 0, v60
	s_waitcnt lgkmcnt(0)
	v_fmac_f32_e32 v63, v61, v62
	v_mul_f32_e32 v60, v60, v62
	ds_read_b32 v62, v196 offset:36864
	ds_read_b32 v61, v197
	s_waitcnt lgkmcnt(1)
	v_mul_f32_e32 v71, v60, v62
	s_waitcnt lgkmcnt(0)
	v_fmac_f32_e32 v61, v63, v62
	ds_read_b32 v64, v198 offset:36864
	ds_read_b32 v63, v199
	s_waitcnt lgkmcnt(1)
	v_mul_f32_e32 v76, v71, v64
	s_waitcnt lgkmcnt(0)
	v_fmac_f32_e32 v63, v61, v64
	ds_read_b32 v66, v200 offset:36864
	ds_read_b32 v61, v201
	s_waitcnt lgkmcnt(0)
	v_fmac_f32_e32 v61, v63, v66
	ds_read_b32 v68, v202 offset:36864
	ds_read_b32 v63, v203
	s_waitcnt lgkmcnt(0)
	v_fmac_f32_e32 v63, v61, v68
	ds_read_b32 v70, v204 offset:36864
	ds_read_b32 v61, v205
	s_waitcnt lgkmcnt(0)
	v_fmac_f32_e32 v61, v63, v70
	ds_read_b32 v72, v206 offset:36864
	ds_read_b32 v63, v207
	s_waitcnt lgkmcnt(0)
	v_fmac_f32_e32 v63, v61, v72
	ds_read_b32 v74, v208 offset:36864
	ds_read_b32 v61, v209
	s_waitcnt lgkmcnt(0)
	v_fmac_f32_e32 v61, v63, v74
	ds_read_b32 v63, v210 offset:36864
	ds_read_b32 v65, v211
	ds_read_b32 v67, v212 offset:36864
	ds_read_b32 v69, v213
	s_waitcnt lgkmcnt(2)
	v_pk_fma_f32 v[60:61], v[60:61], v[62:63], v[64:65]
	s_nop 0
	v_mov_b32_e32 v77, v61
	s_waitcnt lgkmcnt(1)
	v_pk_mul_f32 v[60:61], v[76:77], v[66:67]
	s_waitcnt lgkmcnt(0)
	v_pk_fma_f32 v[64:65], v[76:77], v[66:67], v[68:69]
	v_pk_mul_f32 v[60:61], v[60:61], v[68:69]
	ds_read_b32 v71, v214 offset:36864
	ds_read_b32 v73, v215
	ds_read_b32 v75, v216 offset:36864
	ds_read_b32 v69, v217
	ds_read_b32 v77, v218 offset:36864
	ds_read_b32 v79, v219
	ds_read_b32 v81, v220 offset:36864
	ds_read_b32 v83, v221
	ds_read_b32 v85, v222 offset:36864
	ds_read_b32 v87, v223
	v_mov_b32_e32 v64, v60
	s_waitcnt lgkmcnt(9)
	v_pk_mul_f32 v[60:61], v[60:61], v[70:71]
	s_waitcnt lgkmcnt(8)
	v_pk_fma_f32 v[64:65], v[64:65], v[70:71], v[72:73]
	v_pk_mul_f32 v[60:61], v[60:61], v[72:73]
	v_mov_b32_e32 v62, v63
	v_mov_b32_e32 v61, v65
	s_waitcnt lgkmcnt(7)
	v_pk_mul_f32 v[64:65], v[60:61], v[74:75]
	v_mov_b32_e32 v68, v63
	v_pk_mul_f32 v[62:63], v[64:65], v[62:63]
	s_waitcnt lgkmcnt(6)
	v_pk_fma_f32 v[60:61], v[60:61], v[74:75], v[68:69]
	v_mov_b32_e32 v64, v67
	v_mov_b32_e32 v60, v62
	v_mov_b32_e32 v76, v67
	v_pk_mul_f32 v[62:63], v[62:63], v[64:65]
	v_mov_b32_e32 v64, v71
	v_mov_b32_e32 v78, v71
	v_pk_mul_f32 v[62:63], v[62:63], v[64:65]
	s_waitcnt lgkmcnt(4)
	v_pk_fma_f32 v[60:61], v[60:61], v[76:77], v[78:79]
	v_mov_b32_e32 v80, v75
	v_mov_b32_e32 v63, v61
	s_waitcnt lgkmcnt(3)
	v_pk_mul_f32 v[60:61], v[62:63], v[80:81]
	v_mov_b32_e32 v64, v77
	v_mov_b32_e32 v82, v77
	v_pk_mul_f32 v[60:61], v[60:61], v[64:65]
	s_waitcnt lgkmcnt(2)
	v_pk_fma_f32 v[62:63], v[62:63], v[80:81], v[82:83]
	v_mov_b32_e32 v64, v81
	v_mov_b32_e32 v62, v60
	v_mov_b32_e32 v84, v81
	s_waitcnt lgkmcnt(1)
	v_mov_b32_e32 v86, v85
	v_pk_mul_f32 v[60:61], v[60:61], v[64:65]
	v_mov_b32_e32 v64, v85
	s_waitcnt lgkmcnt(0)
	v_pk_fma_f32 v[62:63], v[62:63], v[84:85], v[86:87]
	v_pk_mul_f32 v[60:61], v[60:61], v[64:65]
	v_add_u32_e32 v62, 0, v109
	v_mov_b32_e32 v61, v63
	v_add_u32_e32 v62, 0x19000, v62
	ds_write_b64 v62, v[60:61]
	v_lshl_add_u32 v60, s24, 2, v153
	s_waitcnt lgkmcnt(0)
	s_barrier
	ds_read_b32 v62, v60
	s_and_saveexec_b64 s[0:1], s[4:5]
	s_cbranch_execz .LBB0_473
	s_mov_b64 s[8:9], 0
	v_mov_b32_e32 v60, v224
	v_mov_b32_e32 v61, v105

; __device__ __forceinline__ float softplusf(float x) { return fmaxf(x, 0.f) + log1pf(__expf(-fabsf(x))); }
; __device__ __forceinline__ void ssd_item(LAS unsigned char* lds, const bf16* proj, const bf16* cxb, bf16* yout, const float* dt_bias, const float* a_log, const float* dskip,
;                                          int gv, int vloc, int hh, int dir) {
;     ...
;         if (tid < 128) DT[tid] = softplusf(dtraw + dtb);
.LBB0_498:
	s_and_saveexec_b64 s[0:1], s[44:45]
	s_cbranch_execz .LBB0_500
	s_waitcnt vmcnt(2)
	v_add_f32_e32 v32, v68, v71
	s_mov_b32 s50, 0xbfb8aa3b
	v_mul_f32_e64 v33, |v32|, s50
	v_exp_f32_e32 v46, v33
	v_max_f32_e32 v47, 0, v32
	s_mov_b32 s50, 0x3f2aaaab
	v_add_f32_e32 v34, 1.0, v46
	v_add_f32_e32 v32, -1.0, v34
	v_sub_f32_e32 v33, v32, v34
	v_sub_f32_e32 v32, v46, v32
	v_add_f32_e32 v33, 1.0, v33
	v_frexp_mant_f32_e32 v35, v34
	v_add_f32_e32 v36, v32, v33
	v_cvt_f64_f32_e32 v[32:33], v34
	v_frexp_exp_i32_f64_e32 v32, v[32:33]
	v_cmp_gt_f32_e32 vcc, s50, v35
	s_mov_b32 s50, 0x3f317218
	s_nop 0
	v_subbrev_co_u32_e32 v40, vcc, 0, v32, vcc
	v_sub_u32_e32 v32, 0, v40
	v_ldexp_f32 v33, v34, v32
	v_ldexp_f32 v32, v36, v32
	v_add_f32_e32 v34, -1.0, v33
	v_add_f32_e32 v36, 1.0, v33
	v_add_f32_e32 v35, 1.0, v34
	v_add_f32_e32 v37, -1.0, v36
	v_sub_f32_e32 v35, v33, v35
	v_sub_f32_e32 v33, v33, v37
	v_add_f32_e32 v35, v32, v35
	v_add_f32_e32 v32, v32, v33
	v_add_f32_e32 v41, v36, v32
	v_rcp_f32_e32 v43, v41
	v_sub_f32_e32 v33, v41, v36
	v_sub_f32_e32 v42, v32, v33
	v_add_f32_e32 v33, v34, v35
	v_mul_f32_e32 v45, v33, v43
	v_sub_f32_e32 v32, v33, v34
	v_mul_f32_e32 v34, v41, v45
	v_fma_f32 v36, v45, v41, -v34
	v_fmac_f32_e32 v36, v45, v42
	v_sub_f32_e32 v44, v35, v32
	v_add_f32_e32 v32, v34, v36
	v_sub_f32_e32 v35, v33, v32
	v_pk_add_f32 v[38:39], v[32:33], v[34:35] neg_lo:[0,1] neg_hi:[0,1]
	v_mov_b32_e32 v37, v32
	v_pk_add_f32 v[32:33], v[38:39], v[36:37] neg_lo:[0,1] neg_hi:[0,1]
	s_nop 0
	v_add_f32_e32 v33, v44, v33
	v_add_f32_e32 v32, v32, v33
	v_add_f32_e32 v33, v35, v32
	v_mul_f32_e32 v44, v43, v33
	v_mul_f32_e32 v34, v41, v44
	v_fma_f32 v36, v44, v41, -v34
	v_fmac_f32_e32 v36, v44, v42
	v_sub_f32_e32 v35, v35, v33
	v_add_f32_e32 v41, v32, v35
	v_add_f32_e32 v32, v34, v36
	v_sub_f32_e32 v35, v33, v32
	v_pk_add_f32 v[38:39], v[32:33], v[34:35] neg_lo:[0,1] neg_hi:[0,1]
	v_mov_b32_e32 v37, v32
	v_pk_add_f32 v[32:33], v[38:39], v[36:37] neg_lo:[0,1] neg_hi:[0,1]
	s_nop 0
	v_add_f32_e32 v33, v41, v33
	v_add_f32_e32 v32, v32, v33
	v_add_f32_e32 v33, v45, v44
	v_add_f32_e32 v32, v35, v32
	v_sub_f32_e32 v34, v33, v45
	v_mul_f32_e32 v32, v43, v32
	v_sub_f32_e32 v34, v44, v34
	v_add_f32_e32 v34, v34, v32
	v_add_f32_e32 v36, v33, v34
	v_mul_f32_e32 v37, v36, v36
	v_fmamk_f32 v32, v37, 0x3e9b6dac, v173
	v_fmaak_f32 v131, v37, v32, 0x3f2aaada
	v_cvt_f32_i32_e32 v32, v40
	v_sub_f32_e32 v33, v36, v33
	v_sub_f32_e32 v33, v34, v33
	v_ldexp_f32 v38, v33, 1
	v_mul_f32_e32 v33, v36, v37
	v_ldexp_f32 v35, v36, 1
	v_pk_mul_f32 v[36:37], v[32:33], v[130:131]
	s_nop 0
	v_fma_f32 v34, v32, s50, -v36
	v_fmac_f32_e32 v34, 0xb102e308, v32
	v_pk_add_f32 v[32:33], v[36:37], v[34:35]
	s_mov_b32 s50, 0x7f800000
	v_sub_f32_e32 v35, v33, v35
	v_sub_f32_e32 v35, v37, v35
	v_add_f32_e32 v39, v38, v35
	v_mov_b32_e32 v38, v36
	v_pk_add_f32 v[36:37], v[32:33], v[36:37] neg_lo:[0,1] neg_hi:[0,1]
	v_pk_add_f32 v[40:41], v[32:33], v[38:39]
	v_mov_b32_e32 v35, v32
	v_mov_b32_e32 v37, v41
	v_pk_add_f32 v[42:43], v[34:35], v[36:37] neg_lo:[0,1] neg_hi:[0,1]
	v_pk_add_f32 v[34:35], v[34:35], v[36:37]
	v_mov_b32_e32 v38, v39
	v_pk_add_f32 v[36:37], v[34:35], v[32:33] op_sel:[1,0] op_sel_hi:[0,1] neg_lo:[0,1] neg_hi:[0,1]
	v_pk_add_f32 v[44:45], v[40:41], v[36:37] op_sel_hi:[1,0] neg_lo:[0,1] neg_hi:[0,1]
	v_mov_b32_e32 v40, v41
	v_mov_b32_e32 v41, v35
	v_pk_mov_b32 v[36:37], v[32:33], v[36:37] op_sel:[1,0]
	v_mov_b32_e32 v39, v32
	v_pk_add_f32 v[36:37], v[40:41], v[36:37] neg_lo:[0,1] neg_hi:[0,1]
	v_mov_b32_e32 v44, v42
	v_pk_add_f32 v[32:33], v[38:39], v[36:37] neg_lo:[0,1] neg_hi:[0,1]
	v_mov_b32_e32 v43, v35
	v_pk_add_f32 v[36:37], v[44:45], v[32:33]
	v_cmp_neq_f32_e32 vcc, s50, v46
	v_pk_add_f32 v[38:39], v[36:37], v[36:37] op_sel:[0,1] op_sel_hi:[1,0]
	s_mov_b32 s50, 0x33800000
	v_pk_add_f32 v[34:35], v[34:35], v[38:39] op_sel:[1,0] op_sel_hi:[0,1]
	v_mov_b32_e32 v37, v34
	v_pk_add_f32 v[40:41], v[36:37], v[42:43] neg_lo:[0,1] neg_hi:[0,1]
	v_mov_b32_e32 v33, v38
	v_sub_f32_e32 v35, v36, v40
	v_pk_add_f32 v[32:33], v[32:33], v[40:41] neg_lo:[0,1] neg_hi:[0,1]
	v_sub_f32_e32 v35, v42, v35
	v_add_f32_e32 v32, v32, v35
	v_add_f32_e32 v32, v32, v33
	v_add_f32_e32 v32, v34, v32
	v_cndmask_b32_e32 v32, v187, v32, vcc
	v_cmp_ngt_f32_e32 vcc, -1.0, v46
	s_nop 1
	v_cndmask_b32_e32 v32, v188, v32, vcc
	v_cmp_neq_f32_e32 vcc, -1.0, v46
	s_nop 1
	v_cndmask_b32_e32 v32, v189, v32, vcc
	v_cmp_lt_f32_e64 vcc, |v46|, s50
	s_nop 1
	v_cndmask_b32_e32 v32, v32, v46, vcc
	v_add_f32_e32 v32, v47, v32
	ds_write_b32 v73, v32
; __device__ __forceinline__ void ssd_item(LAS unsigned char* lds, const bf16* proj, const bf16* cxb, bf16* yout, const float* dt_bias, const float* a_log, const float* dskip,
;                                          int gv, int vloc, int hh, int dir) {
;     ...
;             const float x0 = DT[2 * lane] * aneg, x1 = DT[2 * lane + 1] * aneg;
;             float s = x0 + x1;
; #pragma unroll
;             for (int o = 1; o < 64; o <<= 1) { const float t = __shfl_up(s, o); if (lane >= o) s += t; }
;             tot = __shfl(s, 63);
;             const float p1 = s, p0 = s - x1;
;             if (dir == 0) { ACUM[2 * lane] = p0; ACUM[2 * lane + 1] = p1; }
;             else { ACUM[2 * lane] = tot - p0 + x0; ACUM[2 * lane + 1] = tot - p1 + x1; }
.LBB0_500:
	s_or_b64 exec, exec, s[0:1]
	s_waitcnt lgkmcnt(0)
	s_barrier
	ds_read_b64 v[32:33], v70
	v_readlane_b32 s0, v254, 55
	v_readlane_b32 s1, v254, 56
	s_waitcnt lgkmcnt(0)
	v_pk_mul_f32 v[34:35], v[32:33], v[54:55]
	s_nop 0
	v_add_f32_e32 v34, v34, v35
	s_nop 1
	v_add_f32_dpp v34, v34, v34 row_shr:1 row_mask:0xf bank_mask:0xf
	s_nop 1
	v_add_f32_dpp v34, v34, v34 row_shr:2 row_mask:0xf bank_mask:0xf
	s_nop 1
	v_add_f32_dpp v34, v34, v34 row_shr:4 row_mask:0xf bank_mask:0xf
	s_nop 1
	v_add_f32_dpp v34, v34, v34 row_shr:8 row_mask:0xf bank_mask:0xf
	s_nop 1
	v_add_f32_dpp v34, v34, v34 row_bcast:15 row_mask:0xa bank_mask:0xf
	s_nop 1
	v_add_f32_dpp v34, v34, v34 row_bcast:31 row_mask:0xc bank_mask:0xf
	v_mov_b32_e32 v37, v34
	s_nop 0
	v_readlane_b32 s0, v37, 63
	v_sub_f32_e32 v36, v37, v35
	s_nop 0
	v_mov_b32_e32 v64, s0
	v_pk_add_f32 v[34:35], v[64:65], v[36:37] op_sel_hi:[0,1] neg_lo:[0,1] neg_hi:[0,1]
	v_pk_fma_f32 v[32:33], v[32:33], v[54:55], v[34:35]
	s_nop 0
	v_cndmask_b32_e64 v33, v33, v37, s[38:39]
	v_cndmask_b32_e64 v32, v32, v36, s[38:39]
	ds_write_b64 v74, v[32:33]
	ds_read_b32 v156, v90
	ds_read_b32 v157, v93
	ds_read_b32 v158, v95
	ds_read_b32 v159, v97
	ds_read_b32 v160, v99
	ds_read_b32 v161, v101
	ds_read_b32 v162, v103
	ds_read_b32 v163, v105
	ds_read_b32 v164, v91
	ds_read_b32 v165, v94
	ds_read_b32 v166, v96
	ds_read_b32 v167, v98
	ds_read_b32 v228, v100
	ds_read_b32 v229, v102
	ds_read_b32 v230, v104
	s_waitcnt lgkmcnt(7)
	v_sub_f32_e32 v156, v64, v156
	v_sub_f32_e32 v157, v64, v157
	v_sub_f32_e32 v158, v64, v158
	v_sub_f32_e32 v159, v64, v159
	v_sub_f32_e32 v160, v64, v160
	v_sub_f32_e32 v161, v64, v161
	v_sub_f32_e32 v162, v64, v162
	v_sub_f32_e32 v163, v64, v163
	ds_read_b32 v231, v106
	v_mul_f32_e32 v156, 0x3fb8aa3b, v156
	v_mul_f32_e32 v157, 0x3fb8aa3b, v157
	v_mul_f32_e32 v158, 0x3fb8aa3b, v158
	v_mul_f32_e32 v159, 0x3fb8aa3b, v159
	v_mul_f32_e32 v160, 0x3fb8aa3b, v160
	v_mul_f32_e32 v161, 0x3fb8aa3b, v161
	v_mul_f32_e32 v162, 0x3fb8aa3b, v162
	v_mul_f32_e32 v163, 0x3fb8aa3b, v163
	v_exp_f32_e32 v156, v156
	v_exp_f32_e32 v157, v157
	v_exp_f32_e32 v158, v158
	v_exp_f32_e32 v159, v159
	v_exp_f32_e32 v160, v160
	v_exp_f32_e32 v161, v161
	v_exp_f32_e32 v162, v162
	v_exp_f32_e32 v163, v163
	s_waitcnt lgkmcnt(0)
	v_mul_f32_e32 v156, v164, v156
	v_mul_f32_e32 v157, v165, v157
	v_mul_f32_e32 v158, v166, v158
	v_mul_f32_e32 v159, v167, v159
	v_mul_f32_e32 v160, v228, v160
	v_mul_f32_e32 v161, v229, v161
	v_mul_f32_e32 v162, v230, v162
	v_mul_f32_e32 v163, v231, v163
	s_and_saveexec_b64 vcc, s[42:43]
	s_cbranch_execz .LBB0_539
	s_and_saveexec_b64 s[0:1], s[40:41]
	s_xor_b64 s[0:1], exec, s[0:1]
	s_cbranch_execnz .LBB0_553
	s_andn2_saveexec_b64 s[0:1], s[0:1]
	s_cbranch_execnz .LBB0_558

.LBB0_539:
	s_or_b64 exec, exec, vcc
	s_andn2_b64 vcc, exec, s[34:35]
	s_cbranch_vccnz .LBB0_545
	v_readlane_b32 s0, v254, 54
	s_add_i32 s0, s57, s0
	s_lshl_b32 s34, s0, 7
	v_readlane_b32 s0, v254, 53
	s_add_i32 s34, s34, s0
	s_and_saveexec_b64 s[0:1], s[42:43]
	s_cbranch_execz .LBB0_542
	s_waitcnt vmcnt(3)
	v_add_u32_e32 v26, s34, v69
	s_movk_i32 s35, 0x600
	v_mad_i64_i32 v[0:1], s[50:51], v26, s35, v[50:51]
	v_or_b32_e32 v2, 1, v26
	v_or_b32_e32 v8, 2, v26
	v_or_b32_e32 v10, 3, v26
	v_or_b32_e32 v16, 4, v26
	v_or_b32_e32 v18, 5, v26
	v_or_b32_e32 v24, 6, v26
	v_or_b32_e32 v26, 7, v26
	v_mad_i64_i32 v[4:5], s[50:51], v2, s35, v[50:51]
	v_mad_i64_i32 v[8:9], s[50:51], v8, s35, v[50:51]
	v_mad_i64_i32 v[12:13], s[50:51], v10, s35, v[50:51]
	v_mad_i64_i32 v[16:17], s[50:51], v16, s35, v[50:51]
	v_mad_i64_i32 v[20:21], s[50:51], v18, s35, v[50:51]
	v_mad_i64_i32 v[24:25], s[50:51], v24, s35, v[50:51]
	s_waitcnt vmcnt(2)
	v_mad_i64_i32 v[28:29], s[50:51], v26, s35, v[50:51]
	global_load_dwordx4 v[0:3], v[0:1], off
	s_nop 0
	global_load_dwordx4 v[4:7], v[4:5], off
	s_nop 0
	global_load_dwordx4 v[8:11], v[8:9], off
	s_nop 0
	global_load_dwordx4 v[12:15], v[12:13], off
	s_nop 0
	global_load_dwordx4 v[16:19], v[16:17], off
	s_nop 0
	global_load_dwordx4 v[20:23], v[20:21], off
	s_nop 0
	global_load_dwordx4 v[24:27], v[24:25], off
	s_nop 0
	global_load_dwordx4 v[28:31], v[28:29], off

; #define LAS __attribute__((address_space(3)))
; __device__ __forceinline__ unsigned pk2(float lo, float hi) { return pg8::cvt_pk_bf16(lo, hi); }
; #define MFMA16(a, b, c) __builtin_amdgcn_mfma_f32_16x16x32_bf16((a), (b), (c), 0, 0, 0)
; __device__ __forceinline__ void ssd_item(LAS unsigned char* lds, const bf16* proj, const bf16* cxb, bf16* yout, const float* dt_bias, const float* a_log, const float* dskip,
;                                          int gv, int vloc, int hh, int dir) {
;     ...
;                     u32x2 pk; pk.x = raw[od][2 * hc]; pk.y = raw[od][2 * hc + 1];
;                     if (sec == 0) pv[od & 3] = pk;
;                     else if (sec == 1) { *(LAS u32x2*)(BN + (i0 + od) * LDS_ + c8 + 4 * hc) = pk; const float wr = __expf(tot - ACUM[i0 + od]) * DT[i0 + od];
;                         u32x2 pw; pw.x = pk2(bflo(pk.x) * wr, bfhi(pk.x) * wr); pw.y = pk2(bflo(pk.y) * wr, bfhi(pk.y) * wr); pv[od & 3] = pw; }
;                     else *(LAS u32x2*)(CN + (i0 + od) * LDS_ + c8 + 4 * hc) = pk;
;     ...
;             bf16* yo = yout + (size_t)(lrow0 + qi) * YLD + 512 + 64 * hh + 4 * fq;
; #pragma unroll
;             for (int pt = 0; pt < 4; ++pt) {
;                 if (dir == 0) {
; #pragma unroll
;                     for (int e = 0; e < 4; ++e) Y[pt][e] += dsk * bf2f(XST[(16 * pt + 4 * fq + e) * LDL + qi]);
;                 }
;                 u32x2 w; w.x = pk2(Y[pt][0], Y[pt][1]); w.y = pk2(Y[pt][2], Y[pt][3]); *(u32x2*)(yo + 16 * pt) = w;
;             }
;         }
;         {
;             const float et = __expf(tot);
;             Hc[0] *= et; Hc[1] *= et;
; #pragma unroll
;             for (int ks = 0; ks < 4; ++ks) {
;                 const bf16x8 xf = ldfrag(XST + (16 * (wid & 3) + fr) * LDL + 32 * ks + 8 * fq);
; #pragma unroll
;                 for (int j2 = 0; j2 < 2; ++j2) Hc[j2] = MFMA16(ldfrag(BTW + (16 * (2 * (wid >> 2) + j2) + fr) * LDL + 32 * ks + 8 * fq), xf, Hc[j2]);
;             }
.Lssd_nodskip:
	v_lshl_add_u32 v66, s57, 7, v80
	s_movk_i32 s0, 0xc00
	v_mad_i64_i32 v[66:67], s[0:1], v66, s0, v[52:53]
	ds_read_b128 v[212:215], v81
	ds_read_b128 v[216:219], v81 offset:64
	ds_read_b128 v[220:223], v81 offset:128
	ds_read_b128 v[224:227], v81 offset:192
	ds_read_b128 v[156:159], v132 offset:54272
	ds_read_b128 v[160:163], v133 offset:54272
	ds_read_b128 v[164:167], v132 offset:54336
	ds_read_b128 v[228:231], v133 offset:54336
	ds_read_b128 v[232:235], v132 offset:54400
	ds_read_b128 v[236:239], v133 offset:54400
	ds_read_b128 v[240:243], v132 offset:54464
	ds_read_b128 v[244:247], v133 offset:54464
	v_bfe_u32 v152, v170, 4, 1
	v_mov_b32_e32 v153, 0
	v_mul_u32_u24_e32 v152, 24, v152
	v_lshl_add_u64 v[66:67], v[66:67], 0, v[152:153]
	v_cvt_pk_bf16_f32 v144, v196, v197
	v_cvt_pk_bf16_f32 v146, v200, v201
	v_cvt_pk_bf16_f32 v145, v198, v199
	v_cvt_pk_bf16_f32 v147, v202, v203
	s_nop 0
	v_permlane16_swap_b32_e32 v144, v146
	v_permlane16_swap_b32_e32 v145, v147
	global_store_dwordx4 v[66:67], v[144:147], off offset:1024
	v_cvt_pk_bf16_f32 v148, v204, v205
	v_cvt_pk_bf16_f32 v150, v208, v209
	v_cvt_pk_bf16_f32 v149, v206, v207
	v_cvt_pk_bf16_f32 v151, v210, v211
	s_nop 0
	v_permlane16_swap_b32_e32 v148, v150
	v_permlane16_swap_b32_e32 v149, v151
	global_store_dwordx4 v[66:67], v[148:151], off offset:1088
	v_mul_f32_e32 v42, 0x3fb8aa3b, v64
	v_exp_f32_e32 v42, v42
	s_nop 0
	v_mul_f32_e32 v32, v60, v42
	v_mul_f32_e32 v33, v61, v42
	v_mul_f32_e32 v34, v62, v42
	v_mul_f32_e32 v35, v63, v42
	v_mul_f32_e32 v36, v58, v42
	v_mul_f32_e32 v37, v59, v42
	v_mul_f32_e32 v38, v56, v42
	v_mul_f32_e32 v39, v57, v42
	s_waitcnt lgkmcnt(7)
	v_mfma_f32_16x16x32_bf16 v[32:35], v[156:159], v[212:215], v[32:35]
	s_waitcnt lgkmcnt(6)
	v_mfma_f32_16x16x32_bf16 v[36:39], v[160:163], v[212:215], v[36:39]
	s_waitcnt lgkmcnt(5)
	v_mfma_f32_16x16x32_bf16 v[32:35], v[164:167], v[216:219], v[32:35]
	s_waitcnt lgkmcnt(4)
	v_mfma_f32_16x16x32_bf16 v[36:39], v[228:231], v[216:219], v[36:39]
	s_waitcnt lgkmcnt(3)
	v_mfma_f32_16x16x32_bf16 v[32:35], v[232:235], v[220:223], v[32:35]
	s_waitcnt lgkmcnt(2)
	v_mfma_f32_16x16x32_bf16 v[36:39], v[236:239], v[220:223], v[36:39]
	s_waitcnt lgkmcnt(1)
	v_mfma_f32_16x16x32_bf16 v[32:35], v[240:243], v[224:227], v[32:35]
	s_waitcnt lgkmcnt(0)
	v_mfma_f32_16x16x32_bf16 v[36:39], v[244:247], v[224:227], v[36:39]
	s_add_i32 s54, s54, 1
	s_add_i32 s52, s52, -1
	s_branch .LBB0_495
.LBB0_553:
	s_and_saveexec_b64 s[50:51], s[46:47]
	s_xor_b64 s[50:51], exec, s[50:51]
	s_cbranch_execz .LBB0_555
	v_add_u32_e32 v32, v75, v89
	s_waitcnt vmcnt(9)
	ds_write_b64 v32, v[0:1] offset:17408
.LBB0_555:
	s_andn2_saveexec_b64 s[50:51], s[50:51]
	s_cbranch_execz .LBB0_557
	v_add_u32_e32 v32, v75, v89
	s_waitcnt vmcnt(9)
	ds_write_b64 v32, v[0:1] offset:35840
	v_and_b32_e32 v34, 0xffff0000, v0
	v_mov_b32_e32 v32, v156
	v_lshlrev_b32_e32 v33, 16, v0
	v_mul_f32_e32 v33, v32, v33
	v_mul_f32_e32 v34, v32, v34
	v_cvt_pk_bf16_f32 v113, v33, v34
	v_lshlrev_b32_e32 v33, 16, v1
	v_and_b32_e32 v34, 0xffff0000, v1
	v_mul_f32_e32 v33, v32, v33
	v_mul_f32_e32 v32, v32, v34
	v_cvt_pk_bf16_f32 v140, v33, v32

; #define LAS __attribute__((address_space(3)))
; __device__ __forceinline__ unsigned pk2(float lo, float hi) { return pg8::cvt_pk_bf16(lo, hi); }
; __device__ __forceinline__ void ssd_item(LAS unsigned char* lds, const bf16* proj, const bf16* cxb, bf16* yout, const float* dt_bias, const float* a_log, const float* dskip,
;                                          int gv, int vloc, int hh, int dir) {
;     ...
;                     u32x2 pk; pk.x = raw[od][2 * hc]; pk.y = raw[od][2 * hc + 1];
;                     if (sec == 0) pv[od & 3] = pk;
;                     else if (sec == 1) { *(LAS u32x2*)(BN + (i0 + od) * LDS_ + c8 + 4 * hc) = pk; const float wr = __expf(tot - ACUM[i0 + od]) * DT[i0 + od];
;                         u32x2 pw; pw.x = pk2(bflo(pk.x) * wr, bfhi(pk.x) * wr); pw.y = pk2(bflo(pk.y) * wr, bfhi(pk.y) * wr); pv[od & 3] = pw; }
;                     else *(LAS u32x2*)(CN + (i0 + od) * LDS_ + c8 + 4 * hc) = pk;
;                     if ((od & 3) == 3 && sec != 2) {
.LBB0_558:
	s_waitcnt vmcnt(9)
	v_mov_b32_e32 v113, v0
	v_mov_b32_e32 v140, v1
	s_or_b64 exec, exec, s[0:1]
	s_and_saveexec_b64 s[0:1], s[40:41]
	s_xor_b64 s[0:1], exec, s[0:1]
	s_cbranch_execz .LBB0_504
.LBB0_559:
	s_and_saveexec_b64 s[50:51], s[46:47]
	s_xor_b64 s[50:51], exec, s[50:51]
	s_cbranch_execz .LBB0_561
	v_add_u32_e32 v32, v75, v89
	s_waitcnt vmcnt(8)
	ds_write_b64 v32, v[4:5] offset:17552
.LBB0_561:
	s_andn2_saveexec_b64 s[50:51], s[50:51]
	s_cbranch_execz .LBB0_563
	v_add_u32_e32 v32, v75, v92
	s_waitcnt vmcnt(8)
	ds_write_b64 v32, v[4:5] offset:35840
	v_and_b32_e32 v34, 0xffff0000, v4
	v_mov_b32_e32 v32, v157
	v_lshlrev_b32_e32 v33, 16, v4
	v_mul_f32_e32 v33, v32, v33
	v_mul_f32_e32 v34, v32, v34
	v_cvt_pk_bf16_f32 v137, v33, v34
	v_lshlrev_b32_e32 v33, 16, v5
	v_and_b32_e32 v34, 0xffff0000, v5
	v_mul_f32_e32 v33, v32, v33
	v_mul_f32_e32 v32, v32, v34
	v_cvt_pk_bf16_f32 v141, v33, v32

; #define LAS __attribute__((address_space(3)))
; __device__ __forceinline__ unsigned pk2(float lo, float hi) { return pg8::cvt_pk_bf16(lo, hi); }
; __device__ __forceinline__ void ssd_item(LAS unsigned char* lds, const bf16* proj, const bf16* cxb, bf16* yout, const float* dt_bias, const float* a_log, const float* dskip,
;                                          int gv, int vloc, int hh, int dir) {
;     ...
;                     u32x2 pk; pk.x = raw[od][2 * hc]; pk.y = raw[od][2 * hc + 1];
;                     if (sec == 0) pv[od & 3] = pk;
;                     else if (sec == 1) { *(LAS u32x2*)(BN + (i0 + od) * LDS_ + c8 + 4 * hc) = pk; const float wr = __expf(tot - ACUM[i0 + od]) * DT[i0 + od];
;                         u32x2 pw; pw.x = pk2(bflo(pk.x) * wr, bfhi(pk.x) * wr); pw.y = pk2(bflo(pk.y) * wr, bfhi(pk.y) * wr); pv[od & 3] = pw; }
;                     else *(LAS u32x2*)(CN + (i0 + od) * LDS_ + c8 + 4 * hc) = pk;
;                     if ((od & 3) == 3 && sec != 2) {
.LBB0_564:
	s_waitcnt vmcnt(8)
	v_mov_b32_e32 v137, v4
	v_mov_b32_e32 v141, v5
	s_or_b64 exec, exec, s[0:1]
	s_and_saveexec_b64 s[0:1], s[40:41]
	s_xor_b64 s[0:1], exec, s[0:1]
	s_cbranch_execz .LBB0_506
.LBB0_565:
	s_and_saveexec_b64 s[50:51], s[46:47]
	s_xor_b64 s[50:51], exec, s[50:51]
	s_cbranch_execz .LBB0_567
	v_add_u32_e32 v32, v75, v89
	s_waitcnt vmcnt(7)
	ds_write_b64 v32, v[8:9] offset:17696
.LBB0_567:
	s_andn2_saveexec_b64 s[50:51], s[50:51]
	s_cbranch_execz .LBB0_569
	v_add_u32_e32 v32, v75, v92
	s_waitcnt vmcnt(7)
	ds_write_b64 v32, v[8:9] offset:35984
	v_and_b32_e32 v34, 0xffff0000, v8
	v_mov_b32_e32 v32, v158
	v_lshlrev_b32_e32 v33, 16, v8
	v_mul_f32_e32 v33, v32, v33
	v_mul_f32_e32 v34, v32, v34
	v_cvt_pk_bf16_f32 v138, v33, v34
	v_lshlrev_b32_e32 v33, 16, v9
	v_and_b32_e32 v34, 0xffff0000, v9
	v_mul_f32_e32 v33, v32, v33
	v_mul_f32_e32 v32, v32, v34
	v_cvt_pk_bf16_f32 v142, v33, v32

; #define LAS __attribute__((address_space(3)))
; __device__ __forceinline__ unsigned pk2(float lo, float hi) { return pg8::cvt_pk_bf16(lo, hi); }
; __device__ __forceinline__ void ssd_item(LAS unsigned char* lds, const bf16* proj, const bf16* cxb, bf16* yout, const float* dt_bias, const float* a_log, const float* dskip,
;                                          int gv, int vloc, int hh, int dir) {
;     ...
;                     u32x2 pk; pk.x = raw[od][2 * hc]; pk.y = raw[od][2 * hc + 1];
;                     if (sec == 0) pv[od & 3] = pk;
;                     else if (sec == 1) { *(LAS u32x2*)(BN + (i0 + od) * LDS_ + c8 + 4 * hc) = pk; const float wr = __expf(tot - ACUM[i0 + od]) * DT[i0 + od];
;                         u32x2 pw; pw.x = pk2(bflo(pk.x) * wr, bfhi(pk.x) * wr); pw.y = pk2(bflo(pk.y) * wr, bfhi(pk.y) * wr); pv[od & 3] = pw; }
;                     else *(LAS u32x2*)(CN + (i0 + od) * LDS_ + c8 + 4 * hc) = pk;
;                     if ((od & 3) == 3 && sec != 2) {
.LBB0_570:
	s_waitcnt vmcnt(7)
	v_mov_b32_e32 v138, v8
	v_mov_b32_e32 v142, v9
	s_or_b64 exec, exec, s[0:1]
	s_and_saveexec_b64 s[0:1], s[40:41]
	s_xor_b64 s[0:1], exec, s[0:1]
	s_cbranch_execz .LBB0_508
.LBB0_571:
	s_and_saveexec_b64 s[50:51], s[46:47]
	s_xor_b64 s[50:51], exec, s[50:51]
	s_cbranch_execz .LBB0_573
	v_add_u32_e32 v32, v75, v89
	s_waitcnt vmcnt(6)
	ds_write_b64 v32, v[12:13] offset:17840
.LBB0_573:
	s_andn2_saveexec_b64 s[50:51], s[50:51]
	s_cbranch_execz .LBB0_575
	v_add_u32_e32 v32, v75, v92
	s_waitcnt vmcnt(6)
	ds_write_b64 v32, v[12:13] offset:36128
	v_and_b32_e32 v34, 0xffff0000, v12
	v_mov_b32_e32 v32, v159
	v_lshlrev_b32_e32 v33, 16, v12
	v_mul_f32_e32 v33, v32, v33
	v_mul_f32_e32 v34, v32, v34
	v_cvt_pk_bf16_f32 v139, v33, v34
	v_lshlrev_b32_e32 v33, 16, v13
	v_and_b32_e32 v34, 0xffff0000, v13
	v_mul_f32_e32 v33, v32, v33
	v_mul_f32_e32 v32, v32, v34
	v_cvt_pk_bf16_f32 v143, v33, v32

; #define LAS __attribute__((address_space(3)))
; __device__ __forceinline__ unsigned pk2(float lo, float hi) { return pg8::cvt_pk_bf16(lo, hi); }
; __device__ __forceinline__ void ssd_item(LAS unsigned char* lds, const bf16* proj, const bf16* cxb, bf16* yout, const float* dt_bias, const float* a_log, const float* dskip,
;                                          int gv, int vloc, int hh, int dir) {
;     ...
;                     u32x2 pk; pk.x = raw[od][2 * hc]; pk.y = raw[od][2 * hc + 1];
;                     if (sec == 0) pv[od & 3] = pk;
;                     else if (sec == 1) { *(LAS u32x2*)(BN + (i0 + od) * LDS_ + c8 + 4 * hc) = pk; const float wr = __expf(tot - ACUM[i0 + od]) * DT[i0 + od];
;                         u32x2 pw; pw.x = pk2(bflo(pk.x) * wr, bfhi(pk.x) * wr); pw.y = pk2(bflo(pk.y) * wr, bfhi(pk.y) * wr); pv[od & 3] = pw; }
;                     else *(LAS u32x2*)(CN + (i0 + od) * LDS_ + c8 + 4 * hc) = pk;
;                     if ((od & 3) == 3 && sec != 2) {
.LBB0_576:
	s_waitcnt vmcnt(6)
	v_mov_b32_e32 v139, v12
	v_mov_b32_e32 v143, v13
	s_or_b64 exec, exec, s[0:1]
	s_and_saveexec_b64 s[0:1], s[48:49]
	s_cbranch_execz .LBB0_510

; #define LAS __attribute__((address_space(3)))
; __device__ __forceinline__ unsigned pk2(float lo, float hi) { return pg8::cvt_pk_bf16(lo, hi); }
; __device__ __forceinline__ void ssd_item(LAS unsigned char* lds, const bf16* proj, const bf16* cxb, bf16* yout, const float* dt_bias, const float* a_log, const float* dskip,
;                                          int gv, int vloc, int hh, int dir) {
;     ...
;                     u32x2 pk; pk.x = raw[od][2 * hc]; pk.y = raw[od][2 * hc + 1];
;                     if (sec == 0) pv[od & 3] = pk;
;                     else if (sec == 1) { *(LAS u32x2*)(BN + (i0 + od) * LDS_ + c8 + 4 * hc) = pk; const float wr = __expf(tot - ACUM[i0 + od]) * DT[i0 + od];
;                         u32x2 pw; pw.x = pk2(bflo(pk.x) * wr, bfhi(pk.x) * wr); pw.y = pk2(bflo(pk.y) * wr, bfhi(pk.y) * wr); pv[od & 3] = pw; }
;                     else *(LAS u32x2*)(CN + (i0 + od) * LDS_ + c8 + 4 * hc) = pk;
;                     if ((od & 3) == 3 && sec != 2) {
.LBB0_578:
	s_and_saveexec_b64 s[50:51], s[46:47]
	s_xor_b64 s[50:51], exec, s[50:51]
	s_cbranch_execz .LBB0_580
	v_add_u32_e32 v32, v75, v89
	s_waitcnt vmcnt(5)
	ds_write_b64 v32, v[16:17] offset:17984
.LBB0_580:
	s_andn2_saveexec_b64 s[50:51], s[50:51]
	s_cbranch_execz .LBB0_582
	v_add_u32_e32 v32, v75, v92
	s_waitcnt vmcnt(5)
	ds_write_b64 v32, v[16:17] offset:36272
	v_and_b32_e32 v34, 0xffff0000, v16
	v_mov_b32_e32 v32, v160
	v_lshlrev_b32_e32 v33, 16, v16
	v_mul_f32_e32 v33, v32, v33
	v_mul_f32_e32 v34, v32, v34
	v_cvt_pk_bf16_f32 v113, v33, v34
	v_lshlrev_b32_e32 v33, 16, v17
	v_and_b32_e32 v34, 0xffff0000, v17
	v_mul_f32_e32 v33, v32, v33
	v_mul_f32_e32 v32, v32, v34
	v_cvt_pk_bf16_f32 v140, v33, v32

; #define LAS __attribute__((address_space(3)))
; __device__ __forceinline__ unsigned pk2(float lo, float hi) { return pg8::cvt_pk_bf16(lo, hi); }
; __device__ __forceinline__ void ssd_item(LAS unsigned char* lds, const bf16* proj, const bf16* cxb, bf16* yout, const float* dt_bias, const float* a_log, const float* dskip,
;                                          int gv, int vloc, int hh, int dir) {
;     ...
;                     u32x2 pk; pk.x = raw[od][2 * hc]; pk.y = raw[od][2 * hc + 1];
;                     if (sec == 0) pv[od & 3] = pk;
;                     else if (sec == 1) { *(LAS u32x2*)(BN + (i0 + od) * LDS_ + c8 + 4 * hc) = pk; const float wr = __expf(tot - ACUM[i0 + od]) * DT[i0 + od];
;                         u32x2 pw; pw.x = pk2(bflo(pk.x) * wr, bfhi(pk.x) * wr); pw.y = pk2(bflo(pk.y) * wr, bfhi(pk.y) * wr); pv[od & 3] = pw; }
;                     else *(LAS u32x2*)(CN + (i0 + od) * LDS_ + c8 + 4 * hc) = pk;
;                     if ((od & 3) == 3 && sec != 2) {
.LBB0_583:
	s_waitcnt vmcnt(5)
	v_mov_b32_e32 v113, v16
	v_mov_b32_e32 v140, v17
	s_or_b64 exec, exec, s[0:1]
	s_and_saveexec_b64 s[0:1], s[40:41]
	s_xor_b64 s[0:1], exec, s[0:1]
	s_cbranch_execz .LBB0_513
.LBB0_584:
	s_and_saveexec_b64 s[50:51], s[46:47]
	s_xor_b64 s[50:51], exec, s[50:51]
	s_cbranch_execz .LBB0_586
	v_add_u32_e32 v32, v75, v89
	s_waitcnt vmcnt(4)
	ds_write_b64 v32, v[20:21] offset:18128
.LBB0_586:
	s_andn2_saveexec_b64 s[50:51], s[50:51]
	s_cbranch_execz .LBB0_588
	v_add_u32_e32 v32, v75, v92
	s_waitcnt vmcnt(4)
	ds_write_b64 v32, v[20:21] offset:36416
	v_and_b32_e32 v34, 0xffff0000, v20
	v_mov_b32_e32 v32, v161
	v_lshlrev_b32_e32 v33, 16, v20
	v_mul_f32_e32 v33, v32, v33
	v_mul_f32_e32 v34, v32, v34
	v_cvt_pk_bf16_f32 v137, v33, v34
	v_lshlrev_b32_e32 v33, 16, v21
	v_and_b32_e32 v34, 0xffff0000, v21
	v_mul_f32_e32 v33, v32, v33
	v_mul_f32_e32 v32, v32, v34
	v_cvt_pk_bf16_f32 v141, v33, v32

; #define LAS __attribute__((address_space(3)))
; __device__ __forceinline__ unsigned pk2(float lo, float hi) { return pg8::cvt_pk_bf16(lo, hi); }
; __device__ __forceinline__ void ssd_item(LAS unsigned char* lds, const bf16* proj, const bf16* cxb, bf16* yout, const float* dt_bias, const float* a_log, const float* dskip,
;                                          int gv, int vloc, int hh, int dir) {
;     ...
;                     u32x2 pk; pk.x = raw[od][2 * hc]; pk.y = raw[od][2 * hc + 1];
;                     if (sec == 0) pv[od & 3] = pk;
;                     else if (sec == 1) { *(LAS u32x2*)(BN + (i0 + od) * LDS_ + c8 + 4 * hc) = pk; const float wr = __expf(tot - ACUM[i0 + od]) * DT[i0 + od];
;                         u32x2 pw; pw.x = pk2(bflo(pk.x) * wr, bfhi(pk.x) * wr); pw.y = pk2(bflo(pk.y) * wr, bfhi(pk.y) * wr); pv[od & 3] = pw; }
;                     else *(LAS u32x2*)(CN + (i0 + od) * LDS_ + c8 + 4 * hc) = pk;
;                     if ((od & 3) == 3 && sec != 2) {
.LBB0_589:
	s_waitcnt vmcnt(4)
	v_mov_b32_e32 v137, v20
	v_mov_b32_e32 v141, v21
	s_or_b64 exec, exec, s[0:1]
	s_and_saveexec_b64 s[0:1], s[40:41]
	s_xor_b64 s[0:1], exec, s[0:1]
	s_cbranch_execz .LBB0_515
.LBB0_590:
	s_and_saveexec_b64 s[50:51], s[46:47]
	s_xor_b64 s[50:51], exec, s[50:51]
	s_cbranch_execz .LBB0_592
	v_add_u32_e32 v32, v75, v89
	s_waitcnt vmcnt(3)
	ds_write_b64 v32, v[24:25] offset:18272
.LBB0_592:
	s_andn2_saveexec_b64 s[50:51], s[50:51]
	s_cbranch_execz .LBB0_594
	v_add_u32_e32 v32, v75, v92
	s_waitcnt vmcnt(3)
	ds_write_b64 v32, v[24:25] offset:36560
	v_and_b32_e32 v34, 0xffff0000, v24
	v_mov_b32_e32 v32, v162
	v_lshlrev_b32_e32 v33, 16, v24
	v_mul_f32_e32 v33, v32, v33
	v_mul_f32_e32 v34, v32, v34
	v_cvt_pk_bf16_f32 v138, v33, v34
	v_lshlrev_b32_e32 v33, 16, v25
	v_and_b32_e32 v34, 0xffff0000, v25
	v_mul_f32_e32 v33, v32, v33
	v_mul_f32_e32 v32, v32, v34
	v_cvt_pk_bf16_f32 v142, v33, v32

; #define LAS __attribute__((address_space(3)))
; __device__ __forceinline__ unsigned pk2(float lo, float hi) { return pg8::cvt_pk_bf16(lo, hi); }
; __device__ __forceinline__ void ssd_item(LAS unsigned char* lds, const bf16* proj, const bf16* cxb, bf16* yout, const float* dt_bias, const float* a_log, const float* dskip,
;                                          int gv, int vloc, int hh, int dir) {
;     ...
;                     u32x2 pk; pk.x = raw[od][2 * hc]; pk.y = raw[od][2 * hc + 1];
;                     if (sec == 0) pv[od & 3] = pk;
;                     else if (sec == 1) { *(LAS u32x2*)(BN + (i0 + od) * LDS_ + c8 + 4 * hc) = pk; const float wr = __expf(tot - ACUM[i0 + od]) * DT[i0 + od];
;                         u32x2 pw; pw.x = pk2(bflo(pk.x) * wr, bfhi(pk.x) * wr); pw.y = pk2(bflo(pk.y) * wr, bfhi(pk.y) * wr); pv[od & 3] = pw; }
;                     else *(LAS u32x2*)(CN + (i0 + od) * LDS_ + c8 + 4 * hc) = pk;
;                     if ((od & 3) == 3 && sec != 2) {
.LBB0_595:
	s_waitcnt vmcnt(3)
	v_mov_b32_e32 v138, v24
	v_mov_b32_e32 v142, v25
	s_or_b64 exec, exec, s[0:1]
	s_and_saveexec_b64 s[0:1], s[40:41]
	s_xor_b64 s[0:1], exec, s[0:1]
	s_cbranch_execz .LBB0_517
.LBB0_596:
	s_and_saveexec_b64 s[50:51], s[46:47]
	s_xor_b64 s[50:51], exec, s[50:51]
	s_cbranch_execz .LBB0_598
	v_add_u32_e32 v32, v75, v89
	s_waitcnt vmcnt(2)
	ds_write_b64 v32, v[28:29] offset:18416
.LBB0_598:
	s_andn2_saveexec_b64 s[50:51], s[50:51]
	s_cbranch_execz .LBB0_600
	v_add_u32_e32 v32, v75, v92
	s_waitcnt vmcnt(2)
	ds_write_b64 v32, v[28:29] offset:36704
	v_and_b32_e32 v34, 0xffff0000, v28
	v_mov_b32_e32 v32, v163
	v_lshlrev_b32_e32 v33, 16, v28
	v_mul_f32_e32 v33, v32, v33
	v_mul_f32_e32 v34, v32, v34
	v_cvt_pk_bf16_f32 v139, v33, v34
	v_lshlrev_b32_e32 v33, 16, v29
	v_and_b32_e32 v34, 0xffff0000, v29
	v_mul_f32_e32 v33, v32, v33
	v_mul_f32_e32 v32, v32, v34
	v_cvt_pk_bf16_f32 v143, v33, v32

; #define LAS __attribute__((address_space(3)))
; __device__ __forceinline__ unsigned pk2(float lo, float hi) { return pg8::cvt_pk_bf16(lo, hi); }
; __device__ __forceinline__ void ssd_item(LAS unsigned char* lds, const bf16* proj, const bf16* cxb, bf16* yout, const float* dt_bias, const float* a_log, const float* dskip,
;                                          int gv, int vloc, int hh, int dir) {
;     ...
;                     u32x2 pk; pk.x = raw[od][2 * hc]; pk.y = raw[od][2 * hc + 1];
;                     if (sec == 0) pv[od & 3] = pk;
;                     else if (sec == 1) { *(LAS u32x2*)(BN + (i0 + od) * LDS_ + c8 + 4 * hc) = pk; const float wr = __expf(tot - ACUM[i0 + od]) * DT[i0 + od];
;                         u32x2 pw; pw.x = pk2(bflo(pk.x) * wr, bfhi(pk.x) * wr); pw.y = pk2(bflo(pk.y) * wr, bfhi(pk.y) * wr); pv[od & 3] = pw; }
;                     else *(LAS u32x2*)(CN + (i0 + od) * LDS_ + c8 + 4 * hc) = pk;
;                     if ((od & 3) == 3 && sec != 2) {
.LBB0_601:
	s_waitcnt vmcnt(2)
	v_mov_b32_e32 v139, v28
	v_mov_b32_e32 v143, v29
	s_or_b64 exec, exec, s[0:1]
	s_and_saveexec_b64 s[0:1], s[48:49]
	s_cbranch_execz .LBB0_519

; #define LAS __attribute__((address_space(3)))
; __device__ __forceinline__ unsigned pk2(float lo, float hi) { return pg8::cvt_pk_bf16(lo, hi); }
; __device__ __forceinline__ void ssd_item(LAS unsigned char* lds, const bf16* proj, const bf16* cxb, bf16* yout, const float* dt_bias, const float* a_log, const float* dskip,
;                                          int gv, int vloc, int hh, int dir) {
;     ...
;                     u32x2 pk; pk.x = raw[od][2 * hc]; pk.y = raw[od][2 * hc + 1];
;                     if (sec == 0) pv[od & 3] = pk;
;                     else if (sec == 1) { *(LAS u32x2*)(BN + (i0 + od) * LDS_ + c8 + 4 * hc) = pk; const float wr = __expf(tot - ACUM[i0 + od]) * DT[i0 + od];
;                         u32x2 pw; pw.x = pk2(bflo(pk.x) * wr, bfhi(pk.x) * wr); pw.y = pk2(bflo(pk.y) * wr, bfhi(pk.y) * wr); pv[od & 3] = pw; }
;                     else *(LAS u32x2*)(CN + (i0 + od) * LDS_ + c8 + 4 * hc) = pk;
;                     if ((od & 3) == 3 && sec != 2) {
.LBB0_603:
	s_and_saveexec_b64 s[50:51], s[46:47]
	s_xor_b64 s[50:51], exec, s[50:51]
	s_cbranch_execz .LBB0_605
	v_add_u32_e32 v32, v75, v89
	s_waitcnt vmcnt(9)
	ds_write_b64 v32, v[2:3] offset:17416
.LBB0_605:
	s_andn2_saveexec_b64 s[50:51], s[50:51]
	s_cbranch_execz .LBB0_607
	v_add_u32_e32 v32, v75, v89
	s_waitcnt vmcnt(9)
	ds_write_b64 v32, v[2:3] offset:35848
	v_and_b32_e32 v34, 0xffff0000, v2
	v_mov_b32_e32 v32, v156
	v_lshlrev_b32_e32 v33, 16, v2
	v_mul_f32_e32 v33, v32, v33
	v_mul_f32_e32 v34, v32, v34
	v_cvt_pk_bf16_f32 v113, v33, v34
	v_lshlrev_b32_e32 v33, 16, v3
	v_and_b32_e32 v34, 0xffff0000, v3
	v_mul_f32_e32 v33, v32, v33
	v_mul_f32_e32 v32, v32, v34
	v_cvt_pk_bf16_f32 v140, v33, v32

; #define LAS __attribute__((address_space(3)))
; __device__ __forceinline__ unsigned pk2(float lo, float hi) { return pg8::cvt_pk_bf16(lo, hi); }
; __device__ __forceinline__ void ssd_item(LAS unsigned char* lds, const bf16* proj, const bf16* cxb, bf16* yout, const float* dt_bias, const float* a_log, const float* dskip,
;                                          int gv, int vloc, int hh, int dir) {
;     ...
;                     u32x2 pk; pk.x = raw[od][2 * hc]; pk.y = raw[od][2 * hc + 1];
;                     if (sec == 0) pv[od & 3] = pk;
;                     else if (sec == 1) { *(LAS u32x2*)(BN + (i0 + od) * LDS_ + c8 + 4 * hc) = pk; const float wr = __expf(tot - ACUM[i0 + od]) * DT[i0 + od];
;                         u32x2 pw; pw.x = pk2(bflo(pk.x) * wr, bfhi(pk.x) * wr); pw.y = pk2(bflo(pk.y) * wr, bfhi(pk.y) * wr); pv[od & 3] = pw; }
;                     else *(LAS u32x2*)(CN + (i0 + od) * LDS_ + c8 + 4 * hc) = pk;
;                     if ((od & 3) == 3 && sec != 2) {
.LBB0_608:
	s_waitcnt vmcnt(9)
	v_mov_b32_e32 v113, v2
	v_mov_b32_e32 v140, v3
	s_or_b64 exec, exec, s[0:1]
	s_and_saveexec_b64 s[0:1], s[40:41]
	s_xor_b64 s[0:1], exec, s[0:1]
	s_cbranch_execz .LBB0_522
.LBB0_609:
	s_and_saveexec_b64 s[50:51], s[46:47]
	s_xor_b64 s[50:51], exec, s[50:51]
	s_cbranch_execz .LBB0_611
	v_add_u32_e32 v32, v75, v89
	s_waitcnt vmcnt(8)
	ds_write_b64 v32, v[6:7] offset:17560
.LBB0_611:
	s_andn2_saveexec_b64 s[50:51], s[50:51]
	s_cbranch_execz .LBB0_613
	v_add_u32_e32 v32, v75, v92
	s_waitcnt vmcnt(8)
	ds_write_b64 v32, v[6:7] offset:35848
	v_and_b32_e32 v34, 0xffff0000, v6
	v_mov_b32_e32 v32, v157
	v_lshlrev_b32_e32 v33, 16, v6
	v_mul_f32_e32 v33, v32, v33
	v_mul_f32_e32 v34, v32, v34
	v_cvt_pk_bf16_f32 v137, v33, v34
	v_lshlrev_b32_e32 v33, 16, v7
	v_and_b32_e32 v34, 0xffff0000, v7
	v_mul_f32_e32 v33, v32, v33
	v_mul_f32_e32 v32, v32, v34
	v_cvt_pk_bf16_f32 v141, v33, v32

; #define LAS __attribute__((address_space(3)))
; __device__ __forceinline__ unsigned pk2(float lo, float hi) { return pg8::cvt_pk_bf16(lo, hi); }
; __device__ __forceinline__ void ssd_item(LAS unsigned char* lds, const bf16* proj, const bf16* cxb, bf16* yout, const float* dt_bias, const float* a_log, const float* dskip,
;                                          int gv, int vloc, int hh, int dir) {
;     ...
;                     u32x2 pk; pk.x = raw[od][2 * hc]; pk.y = raw[od][2 * hc + 1];
;                     if (sec == 0) pv[od & 3] = pk;
;                     else if (sec == 1) { *(LAS u32x2*)(BN + (i0 + od) * LDS_ + c8 + 4 * hc) = pk; const float wr = __expf(tot - ACUM[i0 + od]) * DT[i0 + od];
;                         u32x2 pw; pw.x = pk2(bflo(pk.x) * wr, bfhi(pk.x) * wr); pw.y = pk2(bflo(pk.y) * wr, bfhi(pk.y) * wr); pv[od & 3] = pw; }
;                     else *(LAS u32x2*)(CN + (i0 + od) * LDS_ + c8 + 4 * hc) = pk;
;                     if ((od & 3) == 3 && sec != 2) {
.LBB0_614:
	s_waitcnt vmcnt(8)
	v_mov_b32_e32 v137, v6
	v_mov_b32_e32 v141, v7
	s_or_b64 exec, exec, s[0:1]
	s_and_saveexec_b64 s[0:1], s[40:41]
	s_xor_b64 s[0:1], exec, s[0:1]
	s_cbranch_execz .LBB0_524
.LBB0_615:
	s_and_saveexec_b64 s[50:51], s[46:47]
	s_xor_b64 s[50:51], exec, s[50:51]
	s_cbranch_execz .LBB0_617
	v_add_u32_e32 v32, v75, v89
	s_waitcnt vmcnt(7)
	ds_write_b64 v32, v[10:11] offset:17704
.LBB0_617:
	s_andn2_saveexec_b64 s[50:51], s[50:51]
	s_cbranch_execz .LBB0_619
	v_add_u32_e32 v32, v75, v92
	s_waitcnt vmcnt(7)
	ds_write_b64 v32, v[10:11] offset:35992
	v_and_b32_e32 v34, 0xffff0000, v10
	v_mov_b32_e32 v32, v158
	v_lshlrev_b32_e32 v33, 16, v10
	v_mul_f32_e32 v33, v32, v33
	v_mul_f32_e32 v34, v32, v34
	v_cvt_pk_bf16_f32 v138, v33, v34
	v_lshlrev_b32_e32 v33, 16, v11
	v_and_b32_e32 v34, 0xffff0000, v11
	v_mul_f32_e32 v33, v32, v33
	v_mul_f32_e32 v32, v32, v34
	v_cvt_pk_bf16_f32 v142, v33, v32

; #define LAS __attribute__((address_space(3)))
; __device__ __forceinline__ unsigned pk2(float lo, float hi) { return pg8::cvt_pk_bf16(lo, hi); }
; __device__ __forceinline__ void ssd_item(LAS unsigned char* lds, const bf16* proj, const bf16* cxb, bf16* yout, const float* dt_bias, const float* a_log, const float* dskip,
;                                          int gv, int vloc, int hh, int dir) {
;     ...
;                     u32x2 pk; pk.x = raw[od][2 * hc]; pk.y = raw[od][2 * hc + 1];
;                     if (sec == 0) pv[od & 3] = pk;
;                     else if (sec == 1) { *(LAS u32x2*)(BN + (i0 + od) * LDS_ + c8 + 4 * hc) = pk; const float wr = __expf(tot - ACUM[i0 + od]) * DT[i0 + od];
;                         u32x2 pw; pw.x = pk2(bflo(pk.x) * wr, bfhi(pk.x) * wr); pw.y = pk2(bflo(pk.y) * wr, bfhi(pk.y) * wr); pv[od & 3] = pw; }
;                     else *(LAS u32x2*)(CN + (i0 + od) * LDS_ + c8 + 4 * hc) = pk;
;                     if ((od & 3) == 3 && sec != 2) {
.LBB0_620:
	s_waitcnt vmcnt(7)
	v_mov_b32_e32 v138, v10
	v_mov_b32_e32 v142, v11
	s_or_b64 exec, exec, s[0:1]
	s_and_saveexec_b64 s[0:1], s[40:41]
	s_xor_b64 s[0:1], exec, s[0:1]
	s_cbranch_execz .LBB0_526
.LBB0_621:
	s_and_saveexec_b64 s[50:51], s[46:47]
	s_xor_b64 s[50:51], exec, s[50:51]
	s_cbranch_execz .LBB0_623
	v_add_u32_e32 v32, v75, v89
	s_waitcnt vmcnt(6)
	ds_write_b64 v32, v[14:15] offset:17848
.LBB0_623:
	s_andn2_saveexec_b64 s[50:51], s[50:51]
	s_cbranch_execz .LBB0_625
	v_add_u32_e32 v32, v75, v92
	s_waitcnt vmcnt(6)
	ds_write_b64 v32, v[14:15] offset:36136
	v_and_b32_e32 v34, 0xffff0000, v14
	v_mov_b32_e32 v32, v159
	v_lshlrev_b32_e32 v33, 16, v14
	v_mul_f32_e32 v33, v32, v33
	v_mul_f32_e32 v34, v32, v34
	v_cvt_pk_bf16_f32 v139, v33, v34
	v_lshlrev_b32_e32 v33, 16, v15
	v_and_b32_e32 v34, 0xffff0000, v15
	v_mul_f32_e32 v33, v32, v33
	v_mul_f32_e32 v32, v32, v34
	v_cvt_pk_bf16_f32 v143, v33, v32

; #define LAS __attribute__((address_space(3)))
; __device__ __forceinline__ unsigned pk2(float lo, float hi) { return pg8::cvt_pk_bf16(lo, hi); }
; __device__ __forceinline__ void ssd_item(LAS unsigned char* lds, const bf16* proj, const bf16* cxb, bf16* yout, const float* dt_bias, const float* a_log, const float* dskip,
;                                          int gv, int vloc, int hh, int dir) {
;     ...
;                     u32x2 pk; pk.x = raw[od][2 * hc]; pk.y = raw[od][2 * hc + 1];
;                     if (sec == 0) pv[od & 3] = pk;
;                     else if (sec == 1) { *(LAS u32x2*)(BN + (i0 + od) * LDS_ + c8 + 4 * hc) = pk; const float wr = __expf(tot - ACUM[i0 + od]) * DT[i0 + od];
;                         u32x2 pw; pw.x = pk2(bflo(pk.x) * wr, bfhi(pk.x) * wr); pw.y = pk2(bflo(pk.y) * wr, bfhi(pk.y) * wr); pv[od & 3] = pw; }
;                     else *(LAS u32x2*)(CN + (i0 + od) * LDS_ + c8 + 4 * hc) = pk;
;                     if ((od & 3) == 3 && sec != 2) {
.LBB0_626:
	s_waitcnt vmcnt(6)
	v_mov_b32_e32 v139, v14
	v_mov_b32_e32 v143, v15
	s_or_b64 exec, exec, s[0:1]
	s_and_saveexec_b64 s[0:1], s[48:49]
	s_cbranch_execz .LBB0_528

; #define LAS __attribute__((address_space(3)))
; __device__ __forceinline__ unsigned pk2(float lo, float hi) { return pg8::cvt_pk_bf16(lo, hi); }
; __device__ __forceinline__ void ssd_item(LAS unsigned char* lds, const bf16* proj, const bf16* cxb, bf16* yout, const float* dt_bias, const float* a_log, const float* dskip,
;                                          int gv, int vloc, int hh, int dir) {
;     ...
;                     u32x2 pk; pk.x = raw[od][2 * hc]; pk.y = raw[od][2 * hc + 1];
;                     if (sec == 0) pv[od & 3] = pk;
;                     else if (sec == 1) { *(LAS u32x2*)(BN + (i0 + od) * LDS_ + c8 + 4 * hc) = pk; const float wr = __expf(tot - ACUM[i0 + od]) * DT[i0 + od];
;                         u32x2 pw; pw.x = pk2(bflo(pk.x) * wr, bfhi(pk.x) * wr); pw.y = pk2(bflo(pk.y) * wr, bfhi(pk.y) * wr); pv[od & 3] = pw; }
;                     else *(LAS u32x2*)(CN + (i0 + od) * LDS_ + c8 + 4 * hc) = pk;
;                     if ((od & 3) == 3 && sec != 2) {
.LBB0_628:
	s_and_saveexec_b64 s[50:51], s[46:47]
	s_xor_b64 s[50:51], exec, s[50:51]
	s_cbranch_execz .LBB0_630
	v_add_u32_e32 v32, v75, v89
	s_waitcnt vmcnt(5)
	ds_write_b64 v32, v[18:19] offset:17992
.LBB0_630:
	s_andn2_saveexec_b64 s[50:51], s[50:51]
	s_cbranch_execz .LBB0_632
	v_add_u32_e32 v32, v75, v92
	s_waitcnt vmcnt(5)
	ds_write_b64 v32, v[18:19] offset:36280
	v_and_b32_e32 v34, 0xffff0000, v18
	v_mov_b32_e32 v32, v160
	v_lshlrev_b32_e32 v33, 16, v18
	v_mul_f32_e32 v33, v32, v33
	v_mul_f32_e32 v34, v32, v34
	v_cvt_pk_bf16_f32 v113, v33, v34
	v_lshlrev_b32_e32 v33, 16, v19
	v_and_b32_e32 v34, 0xffff0000, v19
	v_mul_f32_e32 v33, v32, v33
	v_mul_f32_e32 v32, v32, v34
	v_cvt_pk_bf16_f32 v140, v33, v32

; #define LAS __attribute__((address_space(3)))
; __device__ __forceinline__ unsigned pk2(float lo, float hi) { return pg8::cvt_pk_bf16(lo, hi); }
; __device__ __forceinline__ void ssd_item(LAS unsigned char* lds, const bf16* proj, const bf16* cxb, bf16* yout, const float* dt_bias, const float* a_log, const float* dskip,
;                                          int gv, int vloc, int hh, int dir) {
;     ...
;                     u32x2 pk; pk.x = raw[od][2 * hc]; pk.y = raw[od][2 * hc + 1];
;                     if (sec == 0) pv[od & 3] = pk;
;                     else if (sec == 1) { *(LAS u32x2*)(BN + (i0 + od) * LDS_ + c8 + 4 * hc) = pk; const float wr = __expf(tot - ACUM[i0 + od]) * DT[i0 + od];
;                         u32x2 pw; pw.x = pk2(bflo(pk.x) * wr, bfhi(pk.x) * wr); pw.y = pk2(bflo(pk.y) * wr, bfhi(pk.y) * wr); pv[od & 3] = pw; }
;                     else *(LAS u32x2*)(CN + (i0 + od) * LDS_ + c8 + 4 * hc) = pk;
;                     if ((od & 3) == 3 && sec != 2) {
.LBB0_633:
	s_waitcnt vmcnt(5)
	v_mov_b32_e32 v113, v18
	v_mov_b32_e32 v140, v19
	s_or_b64 exec, exec, s[0:1]
	s_and_saveexec_b64 s[0:1], s[40:41]
	s_xor_b64 s[0:1], exec, s[0:1]
	s_cbranch_execz .LBB0_531
.LBB0_634:
	s_and_saveexec_b64 s[50:51], s[46:47]
	s_xor_b64 s[50:51], exec, s[50:51]
	s_cbranch_execz .LBB0_636
	v_add_u32_e32 v32, v75, v89
	s_waitcnt vmcnt(4)
	ds_write_b64 v32, v[22:23] offset:18136
.LBB0_636:
	s_andn2_saveexec_b64 s[50:51], s[50:51]
	s_cbranch_execz .LBB0_638
	v_add_u32_e32 v32, v75, v92
	s_waitcnt vmcnt(4)
	ds_write_b64 v32, v[22:23] offset:36424
	v_and_b32_e32 v34, 0xffff0000, v22
	v_mov_b32_e32 v32, v161
	v_lshlrev_b32_e32 v33, 16, v22
	v_mul_f32_e32 v33, v32, v33
	v_mul_f32_e32 v34, v32, v34
	v_cvt_pk_bf16_f32 v137, v33, v34
	v_lshlrev_b32_e32 v33, 16, v23
	v_and_b32_e32 v34, 0xffff0000, v23
	v_mul_f32_e32 v33, v32, v33
	v_mul_f32_e32 v32, v32, v34
	v_cvt_pk_bf16_f32 v141, v33, v32

; #define LAS __attribute__((address_space(3)))
; __device__ __forceinline__ unsigned pk2(float lo, float hi) { return pg8::cvt_pk_bf16(lo, hi); }
; __device__ __forceinline__ void ssd_item(LAS unsigned char* lds, const bf16* proj, const bf16* cxb, bf16* yout, const float* dt_bias, const float* a_log, const float* dskip,
;                                          int gv, int vloc, int hh, int dir) {
;     ...
;                     u32x2 pk; pk.x = raw[od][2 * hc]; pk.y = raw[od][2 * hc + 1];
;                     if (sec == 0) pv[od & 3] = pk;
;                     else if (sec == 1) { *(LAS u32x2*)(BN + (i0 + od) * LDS_ + c8 + 4 * hc) = pk; const float wr = __expf(tot - ACUM[i0 + od]) * DT[i0 + od];
;                         u32x2 pw; pw.x = pk2(bflo(pk.x) * wr, bfhi(pk.x) * wr); pw.y = pk2(bflo(pk.y) * wr, bfhi(pk.y) * wr); pv[od & 3] = pw; }
;                     else *(LAS u32x2*)(CN + (i0 + od) * LDS_ + c8 + 4 * hc) = pk;
;                     if ((od & 3) == 3 && sec != 2) {
.LBB0_639:
	s_waitcnt vmcnt(4)
	v_mov_b32_e32 v137, v22
	v_mov_b32_e32 v141, v23
	s_or_b64 exec, exec, s[0:1]
	s_and_saveexec_b64 s[0:1], s[40:41]
	s_xor_b64 s[0:1], exec, s[0:1]
	s_cbranch_execz .LBB0_533
.LBB0_640:
	s_and_saveexec_b64 s[50:51], s[46:47]
	s_xor_b64 s[50:51], exec, s[50:51]
	s_cbranch_execz .LBB0_642
	v_add_u32_e32 v32, v75, v89
	s_waitcnt vmcnt(3)
	ds_write_b64 v32, v[26:27] offset:18280
.LBB0_642:
	s_andn2_saveexec_b64 s[50:51], s[50:51]
	s_cbranch_execz .LBB0_644
	v_add_u32_e32 v32, v75, v92
	s_waitcnt vmcnt(3)
	ds_write_b64 v32, v[26:27] offset:36568
	v_and_b32_e32 v34, 0xffff0000, v26
	v_mov_b32_e32 v32, v162
	v_lshlrev_b32_e32 v33, 16, v26
	v_mul_f32_e32 v33, v32, v33
	v_mul_f32_e32 v34, v32, v34
	v_cvt_pk_bf16_f32 v138, v33, v34
	v_lshlrev_b32_e32 v33, 16, v27
	v_and_b32_e32 v34, 0xffff0000, v27
	v_mul_f32_e32 v33, v32, v33
	v_mul_f32_e32 v32, v32, v34
	v_cvt_pk_bf16_f32 v142, v33, v32

; #define LAS __attribute__((address_space(3)))
; __device__ __forceinline__ unsigned pk2(float lo, float hi) { return pg8::cvt_pk_bf16(lo, hi); }
; __device__ __forceinline__ void ssd_item(LAS unsigned char* lds, const bf16* proj, const bf16* cxb, bf16* yout, const float* dt_bias, const float* a_log, const float* dskip,
;                                          int gv, int vloc, int hh, int dir) {
;     ...
;                     u32x2 pk; pk.x = raw[od][2 * hc]; pk.y = raw[od][2 * hc + 1];
;                     if (sec == 0) pv[od & 3] = pk;
;                     else if (sec == 1) { *(LAS u32x2*)(BN + (i0 + od) * LDS_ + c8 + 4 * hc) = pk; const float wr = __expf(tot - ACUM[i0 + od]) * DT[i0 + od];
;                         u32x2 pw; pw.x = pk2(bflo(pk.x) * wr, bfhi(pk.x) * wr); pw.y = pk2(bflo(pk.y) * wr, bfhi(pk.y) * wr); pv[od & 3] = pw; }
;                     else *(LAS u32x2*)(CN + (i0 + od) * LDS_ + c8 + 4 * hc) = pk;
;                     if ((od & 3) == 3 && sec != 2) {
.LBB0_645:
	s_waitcnt vmcnt(3)
	v_mov_b32_e32 v138, v26
	v_mov_b32_e32 v142, v27
	s_or_b64 exec, exec, s[0:1]
	s_and_saveexec_b64 s[0:1], s[40:41]
	s_xor_b64 s[0:1], exec, s[0:1]
	s_cbranch_execz .LBB0_535
.LBB0_646:
	s_and_saveexec_b64 s[50:51], s[46:47]
	s_xor_b64 s[50:51], exec, s[50:51]
	s_cbranch_execz .LBB0_648
	v_add_u32_e32 v32, v75, v89
	s_waitcnt vmcnt(2)
	ds_write_b64 v32, v[30:31] offset:18424
.LBB0_648:
	s_andn2_saveexec_b64 s[50:51], s[50:51]
	s_cbranch_execz .LBB0_650
	v_add_u32_e32 v32, v75, v92
	s_waitcnt vmcnt(2)
	ds_write_b64 v32, v[30:31] offset:36712
	v_and_b32_e32 v34, 0xffff0000, v30
	v_mov_b32_e32 v32, v163
	v_lshlrev_b32_e32 v33, 16, v30
	v_mul_f32_e32 v33, v32, v33
	v_mul_f32_e32 v34, v32, v34
	v_cvt_pk_bf16_f32 v139, v33, v34
	v_lshlrev_b32_e32 v33, 16, v31
	v_and_b32_e32 v34, 0xffff0000, v31
	v_mul_f32_e32 v33, v32, v33
	v_mul_f32_e32 v32, v32, v34
	v_cvt_pk_bf16_f32 v143, v33, v32

; #define LAS __attribute__((address_space(3)))
; __device__ __forceinline__ unsigned pk2(float lo, float hi) { return pg8::cvt_pk_bf16(lo, hi); }
; __device__ __forceinline__ void ssd_item(LAS unsigned char* lds, const bf16* proj, const bf16* cxb, bf16* yout, const float* dt_bias, const float* a_log, const float* dskip,
;                                          int gv, int vloc, int hh, int dir) {
;     ...
;                     u32x2 pk; pk.x = raw[od][2 * hc]; pk.y = raw[od][2 * hc + 1];
;                     if (sec == 0) pv[od & 3] = pk;
;                     else if (sec == 1) { *(LAS u32x2*)(BN + (i0 + od) * LDS_ + c8 + 4 * hc) = pk; const float wr = __expf(tot - ACUM[i0 + od]) * DT[i0 + od];
;                         u32x2 pw; pw.x = pk2(bflo(pk.x) * wr, bfhi(pk.x) * wr); pw.y = pk2(bflo(pk.y) * wr, bfhi(pk.y) * wr); pv[od & 3] = pw; }
;                     else *(LAS u32x2*)(CN + (i0 + od) * LDS_ + c8 + 4 * hc) = pk;
;                     if ((od & 3) == 3 && sec != 2) {
.LBB0_651:
	s_waitcnt vmcnt(2)
	v_mov_b32_e32 v139, v30
	v_mov_b32_e32 v143, v31
	s_or_b64 exec, exec, s[0:1]
	s_and_saveexec_b64 s[0:1], s[48:49]
	s_cbranch_execnz .LBB0_537
	s_branch .LBB0_538

; #define LAS __attribute__((address_space(3)))
; __device__ __forceinline__ unsigned pk2(float lo, float hi) { return pg8::cvt_pk_bf16(lo, hi); }
; __device__ __forceinline__ void ret_item(LAS unsigned char* lds, const bf16* proj, bf16* yout, int gv, int vloc, int hd, int dir) {
;     ...
;         __syncthreads();
; #pragma unroll
;         for (int ct = 0; ct < 8; ++ct) { u32x2 w; w.x = pk2(R[ct][0], R[ct][1]); w.y = pk2(R[ct][2], R[ct][3]); *(LAS u32x2*)(RT + (16 * ct + fr) * LD + 16 * wid + 4 * fq) = w; }
;     }
.LBB0_659:
	s_barrier
	v_cvt_pk_bf16_f32 v80, v32, v33
	v_cvt_pk_bf16_f32 v81, v34, v35
	ds_write_b64 v211, v[80:81]
	v_cvt_pk_bf16_f32 v80, v52, v53
	v_cvt_pk_bf16_f32 v81, v54, v55
	ds_write_b64 v211, v[80:81] offset:4352
	v_cvt_pk_bf16_f32 v80, v56, v57
	v_cvt_pk_bf16_f32 v81, v58, v59
	ds_write_b64 v211, v[80:81] offset:8704
	v_cvt_pk_bf16_f32 v80, v60, v61
	v_cvt_pk_bf16_f32 v81, v62, v63
	ds_write_b64 v211, v[80:81] offset:13056
	v_cvt_pk_bf16_f32 v80, v64, v65
	v_cvt_pk_bf16_f32 v81, v66, v67
	ds_write_b64 v211, v[80:81] offset:17408
	v_cvt_pk_bf16_f32 v80, v68, v69
	v_cvt_pk_bf16_f32 v81, v70, v71
	ds_write_b64 v211, v[80:81] offset:21760
	v_cvt_pk_bf16_f32 v80, v72, v73
	v_cvt_pk_bf16_f32 v81, v74, v75
	ds_write_b64 v211, v[80:81] offset:26112
	v_cvt_pk_bf16_f32 v80, v76, v77
	v_cvt_pk_bf16_f32 v81, v78, v79
	ds_write_b64 v211, v[80:81] offset:30464
	s_add_i32 s1, s1, 1
	s_add_i32 s16, s16, -1
	s_waitcnt vmcnt(5)
	v_mov_b64_e32 v[94:95], v[46:47]
	v_mov_b64_e32 v[90:91], v[38:39]
	v_mov_b64_e32 v[86:87], v[42:43]
	s_waitcnt vmcnt(4)
	v_mov_b64_e32 v[82:83], v[50:51]
	s_cmp_lg_u32 s1, 64
	v_mov_b64_e32 v[92:93], v[44:45]
	v_mov_b64_e32 v[88:89], v[36:37]
	v_mov_b64_e32 v[84:85], v[40:41]
	v_mov_b64_e32 v[80:81], v[48:49]
	s_cbranch_scc0 .LBB0_427

; __device__ __forceinline__ unsigned pk2(float lo, float hi) { return pg8::cvt_pk_bf16(lo, hi); }
; #define MFMA16(a, b, c) __builtin_amdgcn_mfma_f32_16x16x32_bf16((a), (b), (c), 0, 0, 0)
; __device__ __forceinline__ void ret_item(LAS unsigned char* lds, const bf16* proj, bf16* yout, int gv, int vloc, int hd, int dir) {
;     ...
;             bf16* yo = yout + (size_t)(lrow0 + qi) * YLD + 1024 + 128 * hd + 4 * fq;
; #pragma unroll
;             for (int ct = 0; ct < 8; ++ct) { u32x2 w; w.x = pk2(Y[ct][0], Y[ct][1]); w.y = pk2(Y[ct][2], Y[ct][3]); *(u32x2*)(yo + 16 * ct) = w; }
;         }
; #pragma unroll
;         for (int ct = 0; ct < 8; ++ct) R[ct] *= cdec;
; #pragma unroll
;         for (int ks = 0; ks < 4; ++ks) {
;             const bf16x8 kf = ldfrag(KTW + (16 * wid + fr) * LD + 32 * ks + 8 * fq);
; #pragma unroll
;             for (int ct = 0; ct < 8; ++ct) R[ct] = MFMA16(kf, ldfrag(VT + (16 * ct + fr) * LD + 32 * ks + 8 * fq), R[ct]);
;         }
.LBB0_670:
	v_lshl_add_u32 v84, s17, 7, v150
	s_movk_i32 s6, 0xc00
	v_mad_i64_i32 v[84:85], s[6:7], v84, s6, v[140:141]
	v_bfe_u32 v86, v170, 4, 1
	v_mov_b32_e32 v87, 0
	v_mul_u32_u24_e32 v86, 24, v86
	v_lshl_add_u64 v[84:85], v[84:85], 0, v[86:87]
	v_cvt_pk_bf16_f32 v88, v96, v97
	v_cvt_pk_bf16_f32 v90, v100, v101
	v_cvt_pk_bf16_f32 v89, v98, v99
	v_cvt_pk_bf16_f32 v91, v102, v103
	s_nop 0
	v_permlane16_swap_b32_e32 v88, v90
	v_permlane16_swap_b32_e32 v89, v91
	global_store_dwordx4 v[84:85], v[88:91], off offset:2048
	v_cvt_pk_bf16_f32 v92, v104, v105
	v_cvt_pk_bf16_f32 v94, v108, v109
	v_cvt_pk_bf16_f32 v93, v106, v107
	v_cvt_pk_bf16_f32 v95, v110, v111
	s_nop 0
	v_permlane16_swap_b32_e32 v92, v94
	v_permlane16_swap_b32_e32 v93, v95
	global_store_dwordx4 v[84:85], v[92:95], off offset:2112
	v_cvt_pk_bf16_f32 v88, v112, v113
	v_cvt_pk_bf16_f32 v90, v116, v117
	v_cvt_pk_bf16_f32 v89, v114, v115
	v_cvt_pk_bf16_f32 v91, v118, v119
	s_nop 0
	v_permlane16_swap_b32_e32 v88, v90
	v_permlane16_swap_b32_e32 v89, v91
	global_store_dwordx4 v[84:85], v[88:91], off offset:2176
	v_cvt_pk_bf16_f32 v92, v120, v121
	v_cvt_pk_bf16_f32 v94, v214, v215
	v_cvt_pk_bf16_f32 v93, v122, v123
	v_cvt_pk_bf16_f32 v95, v216, v217
	s_nop 0
	v_permlane16_swap_b32_e32 v92, v94
	v_permlane16_swap_b32_e32 v93, v95
	global_store_dwordx4 v[84:85], v[92:95], off offset:2240
	ds_read_b128 v[80:83], v210 offset:34816
	ds_read_b128 v[96:99], v210 offset:34880
	ds_read_b128 v[100:103], v210 offset:34944
	ds_read_b128 v[104:107], v210 offset:35008
	v_mov_b32_e32 v125, v124
	v_pk_mul_f32 v[34:35], v[124:125], v[34:35]
	v_pk_mul_f32 v[32:33], v[138:139], v[32:33]
	v_pk_mul_f32 v[54:55], v[124:125], v[54:55]
	v_pk_mul_f32 v[52:53], v[138:139], v[52:53]
	v_pk_mul_f32 v[58:59], v[124:125], v[58:59]
	v_pk_mul_f32 v[56:57], v[138:139], v[56:57]
	v_pk_mul_f32 v[62:63], v[124:125], v[62:63]
	v_pk_mul_f32 v[60:61], v[138:139], v[60:61]
	v_pk_mul_f32 v[66:67], v[124:125], v[66:67]
	v_pk_mul_f32 v[64:65], v[138:139], v[64:65]
	v_pk_mul_f32 v[70:71], v[124:125], v[70:71]
	v_pk_mul_f32 v[68:69], v[138:139], v[68:69]
	v_pk_mul_f32 v[74:75], v[124:125], v[74:75]
	v_pk_mul_f32 v[72:73], v[138:139], v[72:73]
	v_pk_mul_f32 v[78:79], v[124:125], v[78:79]
	v_pk_mul_f32 v[76:77], v[138:139], v[76:77]
	ds_read_b128 v[218:221], v212
	ds_read_b128 v[222:225], v212 offset:4352
	ds_read_b128 v[226:229], v212 offset:8704
	ds_read_b128 v[230:233], v212 offset:13056
	ds_read_b128 v[234:237], v212 offset:17408
	ds_read_b128 v[238:241], v212 offset:21760
	ds_read_b128 v[242:245], v212 offset:26112
	ds_read_b128 v[246:249], v212 offset:30464
	s_waitcnt lgkmcnt(7)
	v_mfma_f32_16x16x32_bf16 v[32:35], v[80:83], v[218:221], v[32:35]
	ds_read_b128 v[218:221], v212 offset:64
	s_waitcnt lgkmcnt(7)
	v_mfma_f32_16x16x32_bf16 v[52:55], v[80:83], v[222:225], v[52:55]
	ds_read_b128 v[222:225], v212 offset:4416
	s_waitcnt lgkmcnt(7)
	v_mfma_f32_16x16x32_bf16 v[56:59], v[80:83], v[226:229], v[56:59]
	ds_read_b128 v[226:229], v212 offset:8768
	s_waitcnt lgkmcnt(7)
	v_mfma_f32_16x16x32_bf16 v[60:63], v[80:83], v[230:233], v[60:63]
	ds_read_b128 v[230:233], v212 offset:13120
	s_waitcnt lgkmcnt(7)
	v_mfma_f32_16x16x32_bf16 v[64:67], v[80:83], v[234:237], v[64:67]
	ds_read_b128 v[234:237], v212 offset:17472
	s_waitcnt lgkmcnt(7)
	v_mfma_f32_16x16x32_bf16 v[68:71], v[80:83], v[238:241], v[68:71]
	ds_read_b128 v[238:241], v212 offset:21824
	s_waitcnt lgkmcnt(7)
	v_mfma_f32_16x16x32_bf16 v[72:75], v[80:83], v[242:245], v[72:75]
	ds_read_b128 v[242:245], v212 offset:26176
	s_waitcnt lgkmcnt(7)
	v_mfma_f32_16x16x32_bf16 v[76:79], v[80:83], v[246:249], v[76:79]
	ds_read_b128 v[246:249], v212 offset:30528
	s_waitcnt lgkmcnt(7)
	v_mfma_f32_16x16x32_bf16 v[32:35], v[96:99], v[218:221], v[32:35]
	ds_read_b128 v[218:221], v212 offset:128
	s_waitcnt lgkmcnt(7)
	v_mfma_f32_16x16x32_bf16 v[52:55], v[96:99], v[222:225], v[52:55]
	ds_read_b128 v[222:225], v212 offset:4480
	s_waitcnt lgkmcnt(7)
	v_mfma_f32_16x16x32_bf16 v[56:59], v[96:99], v[226:229], v[56:59]
	ds_read_b128 v[226:229], v212 offset:8832
	s_waitcnt lgkmcnt(7)
	v_mfma_f32_16x16x32_bf16 v[60:63], v[96:99], v[230:233], v[60:63]
	ds_read_b128 v[230:233], v212 offset:13184
	s_waitcnt lgkmcnt(7)
	v_mfma_f32_16x16x32_bf16 v[64:67], v[96:99], v[234:237], v[64:67]
	ds_read_b128 v[234:237], v212 offset:17536
	s_waitcnt lgkmcnt(7)
	v_mfma_f32_16x16x32_bf16 v[68:71], v[96:99], v[238:241], v[68:71]
	ds_read_b128 v[238:241], v212 offset:21888
	s_waitcnt lgkmcnt(7)
	v_mfma_f32_16x16x32_bf16 v[72:75], v[96:99], v[242:245], v[72:75]
	ds_read_b128 v[242:245], v212 offset:26240
	s_waitcnt lgkmcnt(7)
	v_mfma_f32_16x16x32_bf16 v[76:79], v[96:99], v[246:249], v[76:79]
	ds_read_b128 v[246:249], v212 offset:30592
	s_waitcnt lgkmcnt(7)
	v_mfma_f32_16x16x32_bf16 v[32:35], v[100:103], v[218:221], v[32:35]
	ds_read_b128 v[218:221], v212 offset:192
	s_waitcnt lgkmcnt(7)
	v_mfma_f32_16x16x32_bf16 v[52:55], v[100:103], v[222:225], v[52:55]
	ds_read_b128 v[222:225], v212 offset:4544
	s_waitcnt lgkmcnt(7)
	v_mfma_f32_16x16x32_bf16 v[56:59], v[100:103], v[226:229], v[56:59]
	ds_read_b128 v[226:229], v212 offset:8896
	s_waitcnt lgkmcnt(7)
	v_mfma_f32_16x16x32_bf16 v[60:63], v[100:103], v[230:233], v[60:63]
	ds_read_b128 v[230:233], v212 offset:13248
	s_waitcnt lgkmcnt(7)
	v_mfma_f32_16x16x32_bf16 v[64:67], v[100:103], v[234:237], v[64:67]
	ds_read_b128 v[234:237], v212 offset:17600
	s_waitcnt lgkmcnt(7)
	v_mfma_f32_16x16x32_bf16 v[68:71], v[100:103], v[238:241], v[68:71]
	ds_read_b128 v[238:241], v212 offset:21952
	s_waitcnt lgkmcnt(7)
	v_mfma_f32_16x16x32_bf16 v[72:75], v[100:103], v[242:245], v[72:75]
	ds_read_b128 v[242:245], v212 offset:26304
	s_waitcnt lgkmcnt(7)
	v_mfma_f32_16x16x32_bf16 v[76:79], v[100:103], v[246:249], v[76:79]
	ds_read_b128 v[246:249], v212 offset:30656
	s_waitcnt lgkmcnt(7)
	v_mfma_f32_16x16x32_bf16 v[32:35], v[104:107], v[218:221], v[32:35]
	s_waitcnt lgkmcnt(6)
	v_mfma_f32_16x16x32_bf16 v[52:55], v[104:107], v[222:225], v[52:55]
	s_waitcnt lgkmcnt(5)
	v_mfma_f32_16x16x32_bf16 v[56:59], v[104:107], v[226:229], v[56:59]
	s_waitcnt lgkmcnt(4)
	v_mfma_f32_16x16x32_bf16 v[60:63], v[104:107], v[230:233], v[60:63]
	s_waitcnt lgkmcnt(3)
	v_mfma_f32_16x16x32_bf16 v[64:67], v[104:107], v[234:237], v[64:67]
	s_waitcnt lgkmcnt(2)
	v_mfma_f32_16x16x32_bf16 v[68:71], v[104:107], v[238:241], v[68:71]
	s_waitcnt lgkmcnt(1)
	v_mfma_f32_16x16x32_bf16 v[72:75], v[104:107], v[242:245], v[72:75]
	s_waitcnt lgkmcnt(0)
	v_mfma_f32_16x16x32_bf16 v[76:79], v[104:107], v[246:249], v[76:79]
	s_andn2_b64 vcc, exec, s[8:9]
	s_cbranch_vccnz .LBB0_659
; __device__ __forceinline__ void ret_item(LAS unsigned char* lds, const bf16* proj, bf16* yout, int gv, int vloc, int hd, int dir) {
;     ...
;         if (next_reset) {
; #pragma unroll
;             for (int ct = 0; ct < 8; ++ct) R[ct] = (f32x4){0.f, 0.f, 0.f, 0.f};
;         }
	v_mov_b32_e32 v32, 0
	v_mov_b32_e32 v33, v32
	v_mov_b32_e32 v34, v32
	v_mov_b32_e32 v35, v32
	v_mov_b32_e32 v52, v32
	v_mov_b32_e32 v53, v32
	v_mov_b32_e32 v54, v32
	v_mov_b32_e32 v55, v32
	v_mov_b32_e32 v56, v32
	v_mov_b32_e32 v57, v32
	v_mov_b32_e32 v58, v32
	v_mov_b32_e32 v59, v32
	v_mov_b32_e32 v60, v32
	v_mov_b32_e32 v61, v32
	v_mov_b32_e32 v62, v32
	v_mov_b32_e32 v63, v32
	v_mov_b32_e32 v64, v32
	v_mov_b32_e32 v65, v32
	v_mov_b32_e32 v66, v32
	v_mov_b32_e32 v67, v32
	v_mov_b32_e32 v68, v32
	v_mov_b32_e32 v69, v32
	v_mov_b32_e32 v70, v32
	v_mov_b32_e32 v71, v32
	v_mov_b32_e32 v72, v32
	v_mov_b32_e32 v73, v32
	v_mov_b32_e32 v74, v32
	v_mov_b32_e32 v75, v32
	v_mov_b32_e32 v76, v32
	v_mov_b32_e32 v77, v32
	v_mov_b32_e32 v78, v32
	v_mov_b32_e32 v79, v32
	s_branch .LBB0_659
